# GEMM staging layout (P1+P4): 1 KiB LDS block = 8 rows x 128B so each LDS-DMA instruction reads full lines (was 16 rows x 64B); ds_read bases/immediates remapped, bank-conflict-free
# speedup vs baseline: 1.0583x; 1.0029x over previous
; #define PG8_STAGE(bufoff, gbase, voff) do { _Pragma("unroll") for (int _i = 0; _i < 2; ++_i) \
;         __builtin_amdgcn_global_load_lds((const unsigned*)((const char*)(gbase) + (voff)[_i]), (PG8_LAS unsigned*)(lds + (bufoff) + ldsw + _i * 8192), 16, 0, 0); } while (0)
; #define PG8_WAIT_V(n) asm volatile("s_waitcnt vmcnt(" #n ")" ::: "memory")
; #define PG8_BAR __builtin_amdgcn_s_barrier()
; template <class Epi, class Sched, bool ALIGN_EPI = false, bool SP2 = false>
; __device__ __forceinline__ void gemm_phase(PG8_LAS unsigned char* lds, const Gemm g, const Sched& S, const Epi& E) {
;     const int tid = threadIdx.x, wid = __builtin_amdgcn_readfirstlane(tid >> 6), lane = tid & 63, wr = wid >> 2, wc = wid & 3, fr = lane & 15, fq = lane >> 4;
;     const int K = g.K, nt = K / BK;
;     unsigned voffA[2], voffB[2];
; #pragma unroll
;     for (int i = 0; i < 2; ++i) { int R, C; stage_rc(tid * 16 + i * 8192, R, C); const int Rb = Epi::PERM ? ((R & ~31) + perm32(R & 31)) : R;
;         voffA[i] = (unsigned)(R * K + C) * 2u; voffB[i] = (unsigned)(Rb * K + C) * 2u; }
;     const size_t kstep = (size_t)(BK * 2);
;     const size_t hstep = (size_t)HALF * K * 2;
;     const size_t tstep = 2 * hstep;
;     const unsigned ldsw = (unsigned)wid * 1024u;
;     const int aoff = lds_byte(wr * 64 + fr, fq * 8), boff = lds_byte(wc * 32 + fr, fq * 8);
;     ...
;     if constexpr (SP2) {
;         PG8_STAGE(PG8_SB(0, 0), cB, voffB); PG8_STAGE(PG8_SB(0, 1), cB + hstep, voffB); PG8_STAGE(PG8_SA(0, 0), cA, voffA); PG8_STAGE(PG8_SA(0, 1), cA + hstep, voffA);
;         if (wr == 1) PG8_BAR;
;         PG8_WAIT_V(2); PG8_BAR;
;         PG8_STAGE(PG8_SB(1, 0), cB + kstep, voffB); PG8_STAGE(PG8_SA(1, 0), cA + kstep, voffA); PG8_STAGE(PG8_SB(1, 1), cB + hstep + kstep, voffB);
;         PG8_WAIT_V(6); PG8_BAR;
;     } else {
.LBB0_153:
	s_andn2_b64 vcc, exec, s[0:1]
	s_cbranch_vccnz .LBB0_209
	v_bfe_u32 v1, v0, 2, 3
	v_bfe_u32 v2, v0, 5, 1
	v_bfe_u32 v3, v0, 4, 1
	v_and_b32_e32 v4, 3, v0
	v_lshlrev_b32_e32 v3, 1, v3
	v_xor_b32_e32 v4, v4, v3
	v_lshlrev_b32_e32 v4, 4, v4
	v_lshl_or_b32 v4, v2, 6, v4
	v_lshrrev_b32_e32 v5, 6, v0
	v_lshl_or_b32 v6, v5, 3, v1
	v_lshl_or_b32 v251, v6, 11, v4
	v_and_b32_e32 v6, 1, v5
	v_bfe_u32 v7, v5, 1, 1
	v_lshrrev_b32_e32 v5, 2, v5
	v_lshlrev_b32_e32 v5, 5, v5
	v_lshl_or_b32 v5, v6, 4, v5
	v_lshl_or_b32 v5, v7, 2, v5
	v_bfe_u32 v6, v1, 2, 1
	v_lshl_or_b32 v5, v6, 3, v5
	v_and_b32_e32 v6, 3, v1
	v_or_b32_e32 v5, v5, v6
	v_lshl_or_b32 v252, v5, 11, v4
	v_bfe_u32 v1, v0, 4, 2
	v_bfe_u32 v2, v0, 2, 1
	v_lshlrev_b32_e32 v2, 1, v2
	v_xor_b32_e32 v1, v1, v2
	v_lshlrev_b32_e32 v1, 4, v1
	v_and_b32_e32 v2, 7, v0
	v_lshl_or_b32 v1, v2, 6, v1
	v_bfe_u32 v2, v0, 3, 1
	v_lshl_or_b32 v253, v2, 10, v1
	v_lshlrev_b32_e32 v1, 4, v0
	v_and_b32_e32 v2, 32, v0
	v_bitop3_b32 v3, v1, v2, 48 bitop3:0x6c
	v_lshrrev_b32_e32 v2, 1, v0
	v_lshrrev_b32_e32 v5, 5, v0
	s_add_u32 s68, s22, 0x2000000
	v_and_b32_e32 v2, 24, v2
	v_and_b32_e32 v5, 4, v5
	v_bfe_u32 v6, v0, 2, 2
	s_addc_u32 s69, s23, 0
	v_bfe_u32 v13, v0, 2, 4
	v_and_b32_e32 v12, 64, v0
	v_or3_b32 v5, v5, v6, v2
	v_lshrrev_b32_e32 v6, 3, v0
	v_or_b32_e32 v14, 0x2000, v1
	s_add_u32 s70, s22, 0x1000000
	v_or_b32_e32 v4, v3, v12
	v_and_or_b32 v7, v6, 48, v13
	v_and_or_b32 v6, v6, 32, v5
	v_lshrrev_b32_e32 v1, 7, v14
	s_movk_i32 s0, 0x70
	s_addc_u32 s71, s23, 0
	v_mov_b32_e32 v148, v252
	v_and_or_b32 v6, v1, s0, v13
	s_movk_i32 s0, 0x60
	s_lshr_b32 s1, s14, 6
	s_ashr_i32 s5, s4, 31
	s_ashr_i32 s47, s46, 31
	v_and_or_b32 v1, v1, s0, v5
	s_lshr_b32 s0, s14, 8
	s_lshl_b32 s72, s1, 10
	s_lshl_b64 s[10:11], s[4:5], 19
	s_lshl_b64 s[12:13], s[46:47], 19
	s_add_u32 s50, s70, s12
	s_addc_u32 s51, s71, s13
	s_add_i32 s47, s72, 0
	s_add_i32 m0, s47, 0x10000
	v_add_u32_e32 v152, 0x20000, v252
	global_load_lds_dwordx4 v148, s[50:51]
	s_add_i32 m0, s47, 0x12000
	s_add_u32 s12, s50, 0x40000
	global_load_lds_dwordx4 v152, s[50:51]
	s_addc_u32 s13, s51, 0
	s_add_i32 m0, s47, 0x14000
	v_mov_b32_e32 v146, v251
	global_load_lds_dwordx4 v148, s[12:13]
	s_add_i32 m0, s47, 0x16000
	s_add_u32 s48, s68, s10
	s_addc_u32 s49, s69, s11
	s_add_i32 s73, s47, 0x2000
	global_load_lds_dwordx4 v152, s[12:13]
	s_mov_b32 m0, s47
	s_add_u32 s10, s48, 0x40000
	v_add_u32_e32 v150, 0x20000, v251
	global_load_lds_dwordx4 v146, s[48:49]
	s_mov_b32 m0, s73
	s_addc_u32 s11, s49, 0
	s_add_i32 s74, s47, 0x4000
	global_load_lds_dwordx4 v150, s[48:49]
	s_mov_b32 m0, s74
	s_add_i32 s75, s47, 0x6000
	global_load_lds_dwordx4 v146, s[10:11]
	s_mov_b32 m0, s75
	v_mov_b32_e32 v155, 0
	global_load_lds_dwordx4 v150, s[10:11]
	v_mov_b32_e32 v149, v155
	v_mov_b32_e32 v153, v155
	v_mov_b32_e32 v147, v155
	v_mov_b32_e32 v151, v155
	s_cmp_eq_u32 s0, 1
	v_writelane_b32 v250, s78, 0
	s_mov_b32 s76, 0
	s_mov_b32 s77, 0x10000
	v_lshl_add_u64 v[10:11], s[50:51], 0, v[148:149]
	v_lshl_add_u64 v[8:9], s[50:51], 0, v[152:153]
	v_lshl_add_u64 v[4:5], s[48:49], 0, v[146:147]
	s_cselect_b64 s[10:11], -1, 0
	s_cmp_lg_u32 s0, 1
	v_lshl_add_u64 v[6:7], s[48:49], 0, v[150:151]
	v_writelane_b32 v250, s79, 1
	s_cbranch_scc1 .LBB0_156
	s_barrier
.LBB0_156:
	s_add_u32 s78, s22, 0xc000000
	s_mov_b64 s[12:13], 0x80
	s_addc_u32 s79, s23, 0
	s_and_b32 s5, s1, 3
	s_add_i32 m0, s47, 0x18000
	v_lshl_add_u64 v[10:11], v[10:11], 0, s[12:13]
	s_ashr_i32 s80, s3, 31
	s_ashr_i32 s81, s2, 31
	s_lshl_b32 s15, s0, 13
	s_lshl_b32 s1, s1, 5
	s_lshl_b32 s18, s5, 12
	s_waitcnt vmcnt(2)
	s_barrier
	global_load_lds_dwordx4 v[10:11], off
	v_lshl_add_u64 v[8:9], v[8:9], 0, s[12:13]
	s_add_i32 m0, s47, 0x1a000
	s_add_i32 s82, s47, 0x8000
	s_add_i32 s83, s47, 0xa000
	global_load_lds_dwordx4 v[8:9], off
	v_lshl_add_u64 v[4:5], v[4:5], 0, s[12:13]
	s_mov_b32 m0, s82
	s_add_u32 s16, s50, 0x40080
	global_load_lds_dwordx4 v[4:5], off
	v_lshl_add_u64 v[4:5], v[6:7], 0, s[12:13]
	s_mov_b32 m0, s83
	s_addc_u32 s17, s51, 0
	global_load_lds_dwordx4 v[4:5], off
	s_add_i32 m0, s47, 0x1c000
	v_lshl_add_u64 v[4:5], s[16:17], 0, v[148:149]
	global_load_lds_dwordx4 v[4:5], off
	v_lshl_add_u64 v[4:5], s[16:17], 0, v[152:153]
	s_add_i32 m0, s47, 0x1e000
	v_lshlrev_b32_e32 v1, 6, v0
	global_load_lds_dwordx4 v[4:5], off
	v_lshlrev_b32_e32 v5, 1, v2
	s_movk_i32 s16, 0x3c0
	v_and_b32_e32 v4, 15, v0
	v_and_or_b32 v6, v1, s16, v5
	v_lshlrev_b32_e32 v1, 2, v0
	v_and_b32_e32 v7, 32, v1
	v_lshl_or_b32 v1, s0, 6, v4
	v_lshl_or_b32 v4, v4, 6, v5
	s_cmpk_lt_u32 s14, 0x100
	v_or_b32_e32 v8, s15, v253
	s_cselect_b64 s[14:15], -1, 0
	s_and_b32 s17, s1, 32
	v_or_b32_e32 v4, s17, v2
	v_lshlrev_b32_e32 v154, 2, v4
	v_lshl_add_u64 v[4:5], s[22:23], 0, v[154:155]
	s_mov_b64 s[0:1], 0x100000
	v_lshl_add_u64 v[156:157], v[4:5], 0, s[0:1]
	s_mov_b64 s[0:1], 0x500000
	v_lshl_add_u64 v[158:159], v[4:5], 0, s[0:1]
	s_mov_b64 s[0:1], 0x101000
	v_lshl_add_u64 v[160:161], v[4:5], 0, s[0:1]
	s_mov_b64 s[0:1], 0x501000
	v_lshl_add_u64 v[162:163], v[4:5], 0, s[0:1]
	v_lshlrev_b32_e32 v5, 8, v0
	v_or_b32_e32 v181, s18, v253
	v_and_b32_e32 v5, 0x18000, v5
	v_lshlrev_b32_e32 v6, 11, v13
	s_lshl_b32 s5, s5, 6
	v_or3_b32 v5, v3, v5, v6
	s_and_b32 s16, s5, 0x80
	v_mov_b32_e32 v164, v251
	v_lshlrev_b32_e32 v5, 4, v14
	s_waitcnt vmcnt(6)
	s_or_b32 s0, s16, s17
	v_and_b32_e32 v5, 0x38000, v5
	v_or_b32_e32 v4, s0, v2
	v_or3_b32 v3, v3, v5, v6
	s_add_i32 s85, 0, 0x10000
	s_add_i32 s86, 0, 0x14000
	v_or_b32_e32 v182, s5, v2
	v_mov_b32_e32 v165, v155
	v_add_u32_e32 v166, 0x20000, v251
	v_mov_b32_e32 v167, v155
	v_mov_b64_e32 v[168:169], 0x1400
	v_mov_b64_e32 v[170:171], 0x13ff
	s_movk_i32 s84, 0x281
	v_add_u32_e32 v183, s85, v181
	v_add_u32_e32 v184, s86, v181
	v_add_u32_e32 v185, 0, v8
	s_mov_b64 s[16:17], 0x20000
	s_mov_b32 s87, 0x20000
	s_mov_b64 s[18:19], 0x24000
	s_mov_b32 s88, 0x24000
	s_mov_b64 s[20:21], 0x28000
	s_mov_b32 s89, 0x28000
	s_mov_b64 s[24:25], 0x2c000
	s_mov_b32 s90, 0x2c000
	v_lshlrev_b32_e32 v186, 1, v4
	v_lshlrev_b32_e32 v187, 2, v2
	v_mov_b32_e32 v188, 0x358637bd
	s_mov_b32 s91, 0x800000
	v_mov_b32_e32 v189, 0x3db504f3
	v_mov_b32_e32 v190, 0x3e38aa3b
	s_barrier
	s_branch .LBB0_159

; #define PG8_STAGE(bufoff, gbase, voff) do { _Pragma("unroll") for (int _i = 0; _i < 2; ++_i) \
;         __builtin_amdgcn_global_load_lds((const unsigned*)((const char*)(gbase) + (voff)[_i]), (PG8_LAS unsigned*)(lds + (bufoff) + ldsw + _i * 8192), 16, 0, 0); } while (0)
; #define PG8_LDA(dst, b, h) do { _Pragma("unroll") for (int m = 0; m < 4; ++m) _Pragma("unroll") for (int k = 0; k < 2; ++k) dst[m][k] = *(const PG8_LAS bf16x8*)(lds + PG8_SA(b, h) + aoff + m * 2048 + k * 1024); } while (0)
; #define PG8_LDB(dst, b, h) do { _Pragma("unroll") for (int n = 0; n < 2; ++n) _Pragma("unroll") for (int k = 0; k < 2; ++k) dst[n][k] = *(const PG8_LAS bf16x8*)(lds + PG8_SB(b, h) + boff + n * 2048 + k * 1024); } while (0)
; #define PG8_MMA(ai, bj, At, Bt) do { __builtin_amdgcn_s_setprio(1); _Pragma("unroll") for (int m = 0; m < 4; ++m) _Pragma("unroll") for (int n = 0; n < 2; ++n) _Pragma("unroll") for (int k = 0; k < 2; ++k) \
;         acc[ai][bj][m][n] = __builtin_amdgcn_mfma_f32_16x16x32_bf16(Bt[n][k], At[m][k], acc[ai][bj][m][n], 0, 0, 0); __builtin_amdgcn_s_setprio(0); } while (0)
; #define PG8_WAIT_V(n) asm volatile("s_waitcnt vmcnt(" #n ")" ::: "memory")
; #define PG8_WAIT_L(n) asm volatile("s_waitcnt lgkmcnt(" #n ")" ::: "memory")
; #define PG8_BAR __builtin_amdgcn_s_barrier()
; #define PG8_SCHED __builtin_amdgcn_sched_barrier(0)
; template <class Epi, class Sched, bool ALIGN_EPI = false, bool SP2 = false>
; __device__ __forceinline__ void gemm_phase(PG8_LAS unsigned char* lds, const Gemm g, const Sched& S, const Epi& E) {
;     ...
;             PG8_LDB(B0, 0, 0); PG8_LDB(B1, 0, 1); PG8_SCHED; PG8_LDA(At, 0, 0); PG8_STAGE(PG8_SA(1, 1), a1 + hstep, voffA);
;             PG8_WAIT_V(8); PG8_WAIT_L(0); PG8_BAR; PG8_MMA(0, 0, At, B0); PG8_MMA(0, 1, At, B1); PG8_BAR; PG8_SCHED;
;             PG8_LDA(At, 0, 1); PG8_STAGE(PG8_SB(0, 0), b2, voffB); PG8_STAGE(PG8_SB(0, 1), b2 + hstep, voffB); PG8_STAGE(PG8_SA(0, 0), a2, voffA);
;             PG8_WAIT_V(8); PG8_WAIT_L(0); PG8_BAR; PG8_MMA(1, 0, At, B0); PG8_MMA(1, 1, At, B1); PG8_BAR; PG8_SCHED;
.LBB0_162:
	ds_read_b128 v[130:133], v183
	ds_read_b128 v[134:137], v183 offset:512
	ds_read_b128 v[138:141], v183 offset:2048
	ds_read_b128 v[142:145], v183 offset:2560
	ds_read_b128 v[172:175], v184
	ds_read_b128 v[176:179], v184 offset:512
	ds_read_b128 v[192:195], v184 offset:2048
	ds_read_b128 v[196:199], v184 offset:2560
	s_add_u32 s50, s48, 0xfffc0080
	s_addc_u32 s51, s49, -1
	s_cmp_eq_u32 s93, 12
	s_cselect_b32 s65, s5, s51
	s_cselect_b32 s64, s34, s50
	s_cselect_b32 s51, s27, s92
	s_cselect_b32 s50, s35, s41
	s_add_i32 m0, s47, 0xc000
	ds_read_b128 v[200:203], v185
	ds_read_b128 v[204:207], v185 offset:512
	ds_read_b128 v[208:211], v185 offset:2048
	ds_read_b128 v[212:215], v185 offset:2560
	ds_read_b128 v[216:219], v185 offset:4096
	ds_read_b128 v[220:223], v185 offset:4608
	ds_read_b128 v[224:227], v185 offset:6144
	ds_read_b128 v[228:231], v185 offset:6656
	global_load_lds_dwordx4 v164, s[48:49]
	s_add_i32 m0, s47, 0xe000
	s_nop 0
	global_load_lds_dwordx4 v166, s[48:49]
	s_waitcnt vmcnt(8)
	s_waitcnt lgkmcnt(0)
	s_barrier
	s_setprio 1
	s_waitcnt lgkmcnt(0)
	v_mfma_f32_16x16x32_bf16 v[126:129], v[130:133], v[200:203], v[126:129]
	v_mfma_f32_16x16x32_bf16 v[122:125], v[138:141], v[200:203], v[122:125]
	v_mfma_f32_16x16x32_bf16 v[110:113], v[130:133], v[208:211], v[110:113]
	v_mfma_f32_16x16x32_bf16 v[106:109], v[138:141], v[208:211], v[106:109]
	v_mfma_f32_16x16x32_bf16 v[94:97], v[130:133], v[216:219], v[94:97]
	v_mfma_f32_16x16x32_bf16 v[90:93], v[138:141], v[216:219], v[90:93]
	v_mfma_f32_16x16x32_bf16 v[78:81], v[130:133], v[224:227], v[78:81]
	v_mfma_f32_16x16x32_bf16 v[74:77], v[138:141], v[224:227], v[74:77]
	v_mfma_f32_16x16x32_bf16 v[126:129], v[134:137], v[204:207], v[126:129]
	v_mfma_f32_16x16x32_bf16 v[122:125], v[142:145], v[204:207], v[122:125]
	v_mfma_f32_16x16x32_bf16 v[110:113], v[134:137], v[212:215], v[110:113]
	v_mfma_f32_16x16x32_bf16 v[106:109], v[142:145], v[212:215], v[106:109]
	v_mfma_f32_16x16x32_bf16 v[94:97], v[134:137], v[220:223], v[94:97]
	v_mfma_f32_16x16x32_bf16 v[90:93], v[142:145], v[220:223], v[90:93]
	v_mfma_f32_16x16x32_bf16 v[78:81], v[134:137], v[228:231], v[78:81]
	v_mfma_f32_16x16x32_bf16 v[74:77], v[142:145], v[228:231], v[74:77]
	s_setprio 0
	s_setprio 1
	v_mfma_f32_16x16x32_bf16 v[118:121], v[172:175], v[200:203], v[118:121]
	v_mfma_f32_16x16x32_bf16 v[114:117], v[192:195], v[200:203], v[114:117]
	v_mfma_f32_16x16x32_bf16 v[102:105], v[172:175], v[208:211], v[102:105]
	v_mfma_f32_16x16x32_bf16 v[98:101], v[192:195], v[208:211], v[98:101]
	v_mfma_f32_16x16x32_bf16 v[86:89], v[172:175], v[216:219], v[86:89]
	v_mfma_f32_16x16x32_bf16 v[82:85], v[192:195], v[216:219], v[82:85]
	v_mfma_f32_16x16x32_bf16 v[70:73], v[172:175], v[224:227], v[70:73]
	v_mfma_f32_16x16x32_bf16 v[66:69], v[192:195], v[224:227], v[66:69]
	v_mfma_f32_16x16x32_bf16 v[118:121], v[176:179], v[204:207], v[118:121]
	v_mfma_f32_16x16x32_bf16 v[114:117], v[196:199], v[204:207], v[114:117]
	v_mfma_f32_16x16x32_bf16 v[102:105], v[176:179], v[212:215], v[102:105]
	v_mfma_f32_16x16x32_bf16 v[98:101], v[196:199], v[212:215], v[98:101]
	v_mfma_f32_16x16x32_bf16 v[86:89], v[176:179], v[220:223], v[86:89]
	v_mfma_f32_16x16x32_bf16 v[82:85], v[196:199], v[220:223], v[82:85]
	v_mfma_f32_16x16x32_bf16 v[70:73], v[176:179], v[228:231], v[70:73]
	v_mfma_f32_16x16x32_bf16 v[66:69], v[196:199], v[228:231], v[66:69]
	s_setprio 0
	s_barrier
	s_add_i32 s94, s85, s72
	s_mov_b32 m0, s94
	ds_read_b128 v[200:203], v185 offset:16384
	ds_read_b128 v[204:207], v185 offset:16896
	ds_read_b128 v[208:211], v185 offset:18432
	ds_read_b128 v[212:215], v185 offset:18944
	ds_read_b128 v[216:219], v185 offset:20480
	ds_read_b128 v[220:223], v185 offset:20992
	ds_read_b128 v[224:227], v185 offset:22528
	ds_read_b128 v[228:231], v185 offset:23040
	global_load_lds_dwordx4 v148, s[50:51]
	s_add_i32 m0, s94, 0x2000
	s_add_u32 s94, s50, 0x40000
	s_addc_u32 s95, s51, 0
	s_add_i32 s96, s86, s72
	global_load_lds_dwordx4 v152, s[50:51]
	s_mov_b32 m0, s96
	s_nop 0
	global_load_lds_dwordx4 v148, s[94:95]
	s_add_i32 m0, s96, 0x2000
	s_nop 0
	global_load_lds_dwordx4 v152, s[94:95]
	s_mov_b32 m0, s47
	s_nop 0
	global_load_lds_dwordx4 v146, s[64:65]
	s_mov_b32 m0, s73
	s_nop 0
	global_load_lds_dwordx4 v150, s[64:65]
	s_waitcnt vmcnt(8)
	s_waitcnt lgkmcnt(0)
	s_barrier
	s_setprio 1
	s_waitcnt lgkmcnt(0)
	v_mfma_f32_16x16x32_bf16 v[62:65], v[130:133], v[200:203], v[62:65]
	v_mfma_f32_16x16x32_bf16 v[58:61], v[138:141], v[200:203], v[58:61]
	v_mfma_f32_16x16x32_bf16 v[46:49], v[130:133], v[208:211], v[46:49]
	v_mfma_f32_16x16x32_bf16 v[42:45], v[138:141], v[208:211], v[42:45]
	v_mfma_f32_16x16x32_bf16 v[30:33], v[130:133], v[216:219], v[30:33]
	v_mfma_f32_16x16x32_bf16 v[26:29], v[138:141], v[216:219], v[26:29]
	v_mfma_f32_16x16x32_bf16 v[14:17], v[130:133], v[224:227], v[14:17]
	v_mfma_f32_16x16x32_bf16 v[10:13], v[138:141], v[224:227], v[10:13]
	v_mfma_f32_16x16x32_bf16 v[62:65], v[134:137], v[204:207], v[62:65]
	v_mfma_f32_16x16x32_bf16 v[58:61], v[142:145], v[204:207], v[58:61]
	v_mfma_f32_16x16x32_bf16 v[46:49], v[134:137], v[212:215], v[46:49]
	v_mfma_f32_16x16x32_bf16 v[42:45], v[142:145], v[212:215], v[42:45]
	v_mfma_f32_16x16x32_bf16 v[30:33], v[134:137], v[220:223], v[30:33]
	v_mfma_f32_16x16x32_bf16 v[26:29], v[142:145], v[220:223], v[26:29]
	v_mfma_f32_16x16x32_bf16 v[14:17], v[134:137], v[228:231], v[14:17]
	v_mfma_f32_16x16x32_bf16 v[10:13], v[142:145], v[228:231], v[10:13]
	s_setprio 0
	s_setprio 1
	v_mfma_f32_16x16x32_bf16 v[54:57], v[172:175], v[200:203], v[54:57]
	v_mfma_f32_16x16x32_bf16 v[50:53], v[192:195], v[200:203], v[50:53]
	v_mfma_f32_16x16x32_bf16 v[38:41], v[172:175], v[208:211], v[38:41]
	v_mfma_f32_16x16x32_bf16 v[34:37], v[192:195], v[208:211], v[34:37]
	v_mfma_f32_16x16x32_bf16 v[22:25], v[172:175], v[216:219], v[22:25]
	v_mfma_f32_16x16x32_bf16 v[18:21], v[192:195], v[216:219], v[18:21]
	v_mfma_f32_16x16x32_bf16 v[6:9], v[172:175], v[224:227], v[6:9]
	v_mfma_f32_16x16x32_bf16 v[2:5], v[192:195], v[224:227], v[2:5]
	v_mfma_f32_16x16x32_bf16 v[54:57], v[176:179], v[204:207], v[54:57]
	v_mfma_f32_16x16x32_bf16 v[50:53], v[196:199], v[204:207], v[50:53]
	v_mfma_f32_16x16x32_bf16 v[38:41], v[176:179], v[212:215], v[38:41]
	v_mfma_f32_16x16x32_bf16 v[34:37], v[196:199], v[212:215], v[34:37]
	v_mfma_f32_16x16x32_bf16 v[22:25], v[176:179], v[220:223], v[22:25]
	v_mfma_f32_16x16x32_bf16 v[18:21], v[196:199], v[220:223], v[18:21]
	v_mfma_f32_16x16x32_bf16 v[6:9], v[176:179], v[228:231], v[6:9]
	v_mfma_f32_16x16x32_bf16 v[2:5], v[196:199], v[228:231], v[2:5]
	s_setprio 0
	s_barrier
; #define PG8_STAGE(bufoff, gbase, voff) do { _Pragma("unroll") for (int _i = 0; _i < 2; ++_i) \
;         __builtin_amdgcn_global_load_lds((const unsigned*)((const char*)(gbase) + (voff)[_i]), (PG8_LAS unsigned*)(lds + (bufoff) + ldsw + _i * 8192), 16, 0, 0); } while (0)
; #define PG8_LDA(dst, b, h) do { _Pragma("unroll") for (int m = 0; m < 4; ++m) _Pragma("unroll") for (int k = 0; k < 2; ++k) dst[m][k] = *(const PG8_LAS bf16x8*)(lds + PG8_SA(b, h) + aoff + m * 2048 + k * 1024); } while (0)
; #define PG8_LDB(dst, b, h) do { _Pragma("unroll") for (int n = 0; n < 2; ++n) _Pragma("unroll") for (int k = 0; k < 2; ++k) dst[n][k] = *(const PG8_LAS bf16x8*)(lds + PG8_SB(b, h) + boff + n * 2048 + k * 1024); } while (0)
; #define PG8_MMA(ai, bj, At, Bt) do { __builtin_amdgcn_s_setprio(1); _Pragma("unroll") for (int m = 0; m < 4; ++m) _Pragma("unroll") for (int n = 0; n < 2; ++n) _Pragma("unroll") for (int k = 0; k < 2; ++k) \
;         acc[ai][bj][m][n] = __builtin_amdgcn_mfma_f32_16x16x32_bf16(Bt[n][k], At[m][k], acc[ai][bj][m][n], 0, 0, 0); __builtin_amdgcn_s_setprio(0); } while (0)
; #define PG8_WAIT_V(n) asm volatile("s_waitcnt vmcnt(" #n ")" ::: "memory")
; #define PG8_WAIT_L(n) asm volatile("s_waitcnt lgkmcnt(" #n ")" ::: "memory")
; #define PG8_BAR __builtin_amdgcn_s_barrier()
; #define PG8_SCHED __builtin_amdgcn_sched_barrier(0)
; template <class Epi, class Sched, bool ALIGN_EPI = false, bool SP2 = false>
; __device__ __forceinline__ void gemm_phase(PG8_LAS unsigned char* lds, const Gemm g, const Sched& S, const Epi& E) {
;     ...
;             PG8_LDB(B0, 1, 0); PG8_LDB(B1, 1, 1); PG8_SCHED; PG8_LDA(At, 1, 0); PG8_STAGE(PG8_SA(0, 1), a2 + hstep, voffA);
;             PG8_WAIT_V(8); PG8_WAIT_L(0); PG8_BAR; PG8_MMA(0, 0, At, B0); PG8_MMA(0, 1, At, B1); PG8_BAR; PG8_SCHED;
;             PG8_LDA(At, 1, 1); PG8_STAGE(PG8_SB(1, 0), b3, voffB); PG8_STAGE(PG8_SB(1, 1), b3 + hstep, voffB); PG8_STAGE(PG8_SA(1, 0), a3, voffA);
;             PG8_WAIT_V(8); PG8_WAIT_L(0); PG8_BAR; PG8_MMA(1, 0, At, B0); PG8_MMA(1, 1, At, B1); PG8_BAR; PG8_SCHED;
	s_add_i32 s94, 0, 0x18000
	s_add_i32 s95, 0, 0x1c000
	v_add_u32_e32 v142, s94, v181
	v_add_u32_e32 v154, s95, v181
	ds_read_b128 v[130:133], v142
	ds_read_b128 v[134:137], v142 offset:512
	ds_read_b128 v[138:141], v142 offset:2048
	ds_read_b128 v[142:145], v142 offset:2560
	ds_read_b128 v[172:175], v154
	ds_read_b128 v[176:179], v154 offset:512
	ds_read_b128 v[192:195], v154 offset:2048
	ds_read_b128 v[196:199], v154 offset:2560
	s_add_u32 s64, s64, 0x40000
	s_addc_u32 s65, s65, 0
	s_mov_b32 m0, s74
	ds_read_b128 v[200:203], v185 offset:32768
	ds_read_b128 v[204:207], v185 offset:33280
	ds_read_b128 v[208:211], v185 offset:34816
	ds_read_b128 v[212:215], v185 offset:35328
	ds_read_b128 v[216:219], v185 offset:36864
	ds_read_b128 v[220:223], v185 offset:37376
	ds_read_b128 v[224:227], v185 offset:38912
	ds_read_b128 v[228:231], v185 offset:39424
	global_load_lds_dwordx4 v146, s[64:65]
	s_mov_b32 m0, s75
	s_nop 0
	global_load_lds_dwordx4 v150, s[64:65]
	s_waitcnt vmcnt(8)
	s_waitcnt lgkmcnt(0)
	s_barrier
	s_setprio 1
	s_waitcnt lgkmcnt(0)
	v_mfma_f32_16x16x32_bf16 v[126:129], v[130:133], v[200:203], v[126:129]
	v_mfma_f32_16x16x32_bf16 v[122:125], v[138:141], v[200:203], v[122:125]
	v_mfma_f32_16x16x32_bf16 v[110:113], v[130:133], v[208:211], v[110:113]
	v_mfma_f32_16x16x32_bf16 v[106:109], v[138:141], v[208:211], v[106:109]
	v_mfma_f32_16x16x32_bf16 v[94:97], v[130:133], v[216:219], v[94:97]
	v_mfma_f32_16x16x32_bf16 v[90:93], v[138:141], v[216:219], v[90:93]
	v_mfma_f32_16x16x32_bf16 v[78:81], v[130:133], v[224:227], v[78:81]
	v_mfma_f32_16x16x32_bf16 v[74:77], v[138:141], v[224:227], v[74:77]
	v_mfma_f32_16x16x32_bf16 v[126:129], v[134:137], v[204:207], v[126:129]
	v_mfma_f32_16x16x32_bf16 v[122:125], v[142:145], v[204:207], v[122:125]
	v_mfma_f32_16x16x32_bf16 v[110:113], v[134:137], v[212:215], v[110:113]
	v_mfma_f32_16x16x32_bf16 v[106:109], v[142:145], v[212:215], v[106:109]
	v_mfma_f32_16x16x32_bf16 v[94:97], v[134:137], v[220:223], v[94:97]
	v_mfma_f32_16x16x32_bf16 v[90:93], v[142:145], v[220:223], v[90:93]
	v_mfma_f32_16x16x32_bf16 v[78:81], v[134:137], v[228:231], v[78:81]
	v_mfma_f32_16x16x32_bf16 v[74:77], v[142:145], v[228:231], v[74:77]
	s_setprio 0
	s_setprio 1
	v_mfma_f32_16x16x32_bf16 v[118:121], v[172:175], v[200:203], v[118:121]
	v_mfma_f32_16x16x32_bf16 v[114:117], v[192:195], v[200:203], v[114:117]
	v_mfma_f32_16x16x32_bf16 v[102:105], v[172:175], v[208:211], v[102:105]
	v_mfma_f32_16x16x32_bf16 v[98:101], v[192:195], v[208:211], v[98:101]
	v_mfma_f32_16x16x32_bf16 v[86:89], v[172:175], v[216:219], v[86:89]
	v_mfma_f32_16x16x32_bf16 v[82:85], v[192:195], v[216:219], v[82:85]
	v_mfma_f32_16x16x32_bf16 v[70:73], v[172:175], v[224:227], v[70:73]
	v_mfma_f32_16x16x32_bf16 v[66:69], v[192:195], v[224:227], v[66:69]
	v_mfma_f32_16x16x32_bf16 v[118:121], v[176:179], v[204:207], v[118:121]
	v_mfma_f32_16x16x32_bf16 v[114:117], v[196:199], v[204:207], v[114:117]
	v_mfma_f32_16x16x32_bf16 v[102:105], v[176:179], v[212:215], v[102:105]
	v_mfma_f32_16x16x32_bf16 v[98:101], v[196:199], v[212:215], v[98:101]
	v_mfma_f32_16x16x32_bf16 v[86:89], v[176:179], v[220:223], v[86:89]
	v_mfma_f32_16x16x32_bf16 v[82:85], v[196:199], v[220:223], v[82:85]
	v_mfma_f32_16x16x32_bf16 v[70:73], v[176:179], v[228:231], v[70:73]
	v_mfma_f32_16x16x32_bf16 v[66:69], v[196:199], v[228:231], v[66:69]
	s_setprio 0
	s_barrier
	s_add_i32 s96, s94, s72
	s_add_u32 s12, s50, 0x80
	s_addc_u32 s13, s51, 0
	s_mov_b32 m0, s96
	ds_read_b128 v[200:203], v185 offset:49152
	ds_read_b128 v[204:207], v185 offset:49664
	ds_read_b128 v[208:211], v185 offset:51200
	ds_read_b128 v[212:215], v185 offset:51712
	ds_read_b128 v[216:219], v185 offset:53248
	ds_read_b128 v[220:223], v185 offset:53760
	ds_read_b128 v[224:227], v185 offset:55296
	ds_read_b128 v[228:231], v185 offset:55808
	global_load_lds_dwordx4 v148, s[12:13]
	s_add_i32 m0, s96, 0x2000
	s_add_u32 s50, s50, 0x40080
	s_addc_u32 s51, s51, 0
	s_add_i32 s96, s95, s72
	global_load_lds_dwordx4 v152, s[12:13]
	s_mov_b32 m0, s96
	s_nop 0
	global_load_lds_dwordx4 v148, s[50:51]
	s_add_i32 m0, s96, 0x2000
	s_nop 0
	global_load_lds_dwordx4 v152, s[50:51]
	s_add_u32 s64, s64, 0xfffc0080
	s_addc_u32 s65, s65, -1
	s_mov_b32 m0, s82
	s_nop 0
	global_load_lds_dwordx4 v146, s[64:65]
	s_mov_b32 m0, s83
	s_nop 0
	global_load_lds_dwordx4 v150, s[64:65]
	s_waitcnt vmcnt(8)
	s_waitcnt lgkmcnt(0)
	s_barrier
	s_setprio 1
	s_waitcnt lgkmcnt(0)
	v_mfma_f32_16x16x32_bf16 v[62:65], v[130:133], v[200:203], v[62:65]
	v_mfma_f32_16x16x32_bf16 v[58:61], v[138:141], v[200:203], v[58:61]
	v_mfma_f32_16x16x32_bf16 v[46:49], v[130:133], v[208:211], v[46:49]
	v_mfma_f32_16x16x32_bf16 v[42:45], v[138:141], v[208:211], v[42:45]
	v_mfma_f32_16x16x32_bf16 v[30:33], v[130:133], v[216:219], v[30:33]
	v_mfma_f32_16x16x32_bf16 v[26:29], v[138:141], v[216:219], v[26:29]
	v_mfma_f32_16x16x32_bf16 v[14:17], v[130:133], v[224:227], v[14:17]
	v_mfma_f32_16x16x32_bf16 v[10:13], v[138:141], v[224:227], v[10:13]
	v_mfma_f32_16x16x32_bf16 v[62:65], v[134:137], v[204:207], v[62:65]
	v_mfma_f32_16x16x32_bf16 v[58:61], v[142:145], v[204:207], v[58:61]
	v_mfma_f32_16x16x32_bf16 v[46:49], v[134:137], v[212:215], v[46:49]
	v_mfma_f32_16x16x32_bf16 v[42:45], v[142:145], v[212:215], v[42:45]
	v_mfma_f32_16x16x32_bf16 v[30:33], v[134:137], v[220:223], v[30:33]
	v_mfma_f32_16x16x32_bf16 v[26:29], v[142:145], v[220:223], v[26:29]
	v_mfma_f32_16x16x32_bf16 v[14:17], v[134:137], v[228:231], v[14:17]
	v_mfma_f32_16x16x32_bf16 v[10:13], v[142:145], v[228:231], v[10:13]
	s_setprio 0
	s_setprio 1
	v_mfma_f32_16x16x32_bf16 v[54:57], v[172:175], v[200:203], v[54:57]
	v_mfma_f32_16x16x32_bf16 v[50:53], v[192:195], v[200:203], v[50:53]
	v_mfma_f32_16x16x32_bf16 v[38:41], v[172:175], v[208:211], v[38:41]
	v_mfma_f32_16x16x32_bf16 v[34:37], v[192:195], v[208:211], v[34:37]
	v_mfma_f32_16x16x32_bf16 v[22:25], v[172:175], v[216:219], v[22:25]
	v_mfma_f32_16x16x32_bf16 v[18:21], v[192:195], v[216:219], v[18:21]
	v_mfma_f32_16x16x32_bf16 v[6:9], v[172:175], v[224:227], v[6:9]
	v_mfma_f32_16x16x32_bf16 v[2:5], v[192:195], v[224:227], v[2:5]
	v_mfma_f32_16x16x32_bf16 v[54:57], v[176:179], v[204:207], v[54:57]
	v_mfma_f32_16x16x32_bf16 v[50:53], v[196:199], v[204:207], v[50:53]
	v_mfma_f32_16x16x32_bf16 v[38:41], v[176:179], v[212:215], v[38:41]
	v_mfma_f32_16x16x32_bf16 v[34:37], v[196:199], v[212:215], v[34:37]
	v_mfma_f32_16x16x32_bf16 v[22:25], v[176:179], v[220:223], v[22:25]
	v_mfma_f32_16x16x32_bf16 v[18:21], v[196:199], v[220:223], v[18:21]
	v_mfma_f32_16x16x32_bf16 v[6:9], v[176:179], v[228:231], v[6:9]
	v_mfma_f32_16x16x32_bf16 v[2:5], v[196:199], v[228:231], v[2:5]
	s_setprio 0
	s_add_i32 s93, s93, 2
	s_add_u32 s48, s48, 0x100
	s_addc_u32 s49, s49, 0
	s_add_u32 s41, s41, 0x100
	s_addc_u32 s92, s92, 0
	s_cmp_gt_u32 s93, 13
	s_cbranch_scc1 .Lp1_kexit
	s_barrier
	s_branch .LBB0_162

; #define PG8_STAGE(bufoff, gbase, voff) do { _Pragma("unroll") for (int _i = 0; _i < 2; ++_i) \
;         __builtin_amdgcn_global_load_lds((const unsigned*)((const char*)(gbase) + (voff)[_i]), (PG8_LAS unsigned*)(lds + (bufoff) + ldsw + _i * 8192), 16, 0, 0); } while (0)
; #define PG8_LDA(dst, b, h) do { _Pragma("unroll") for (int m = 0; m < 4; ++m) _Pragma("unroll") for (int k = 0; k < 2; ++k) dst[m][k] = *(const PG8_LAS bf16x8*)(lds + PG8_SA(b, h) + aoff + m * 2048 + k * 1024); } while (0)
; #define PG8_LDB(dst, b, h) do { _Pragma("unroll") for (int n = 0; n < 2; ++n) _Pragma("unroll") for (int k = 0; k < 2; ++k) dst[n][k] = *(const PG8_LAS bf16x8*)(lds + PG8_SB(b, h) + boff + n * 2048 + k * 1024); } while (0)
; #define PG8_MMA(ai, bj, At, Bt) do { __builtin_amdgcn_s_setprio(1); _Pragma("unroll") for (int m = 0; m < 4; ++m) _Pragma("unroll") for (int n = 0; n < 2; ++n) _Pragma("unroll") for (int k = 0; k < 2; ++k) \
;         acc[ai][bj][m][n] = __builtin_amdgcn_mfma_f32_16x16x32_bf16(Bt[n][k], At[m][k], acc[ai][bj][m][n], 0, 0, 0); __builtin_amdgcn_s_setprio(0); } while (0)
; #define PG8_WAIT_V(n) asm volatile("s_waitcnt vmcnt(" #n ")" ::: "memory")
; #define PG8_WAIT_L(n) asm volatile("s_waitcnt lgkmcnt(" #n ")" ::: "memory")
; #define PG8_BAR __builtin_amdgcn_s_barrier()
; #define PG8_SCHED __builtin_amdgcn_sched_barrier(0)
; template <class Epi, class Sched, bool ALIGN_EPI = false, bool SP2 = false>
; __device__ __forceinline__ void gemm_phase(PG8_LAS unsigned char* lds, const Gemm g, const Sched& S, const Epi& E) {
;     ...
;             PG8_LDB(B0, 0, 0); PG8_LDB(B1, 0, 1); PG8_SCHED; PG8_LDA(At, 0, 0); PG8_STAGE(PG8_SA(1, 1), a1 + hstep, voffA);
;             PG8_WAIT_V(8); PG8_WAIT_L(0); PG8_BAR; PG8_MMA(0, 0, At, B0); PG8_MMA(0, 1, At, B1); PG8_BAR; PG8_SCHED;
;             PG8_LDA(At, 0, 1); PG8_STAGE(PG8_SB(0, 0), b2, voffB); PG8_STAGE(PG8_SB(0, 1), b2 + hstep, voffB); PG8_STAGE(PG8_SA(0, 0), a2, voffA);
;             PG8_WAIT_V(8); PG8_WAIT_L(0); PG8_BAR; PG8_MMA(1, 0, At, B0); PG8_MMA(1, 1, At, B1); PG8_BAR; PG8_SCHED;
;     ...
;         for (int a = 0; a < 2; ++a)
; #pragma unroll
;             for (int b = 0; b < 2; ++b)
; #pragma unroll
;                 for (int m = 0; m < 4; ++m)
; #pragma unroll
;                     for (int n = 0; n < 2; ++n) acc[a][b][m][n] = (f32x4){0.f, 0.f, 0.f, 0.f};
.Lp1_peel:
	ds_read_b128 v[130:133], v183
	ds_read_b128 v[134:137], v183 offset:512
	ds_read_b128 v[138:141], v183 offset:2048
	ds_read_b128 v[142:145], v183 offset:2560
	ds_read_b128 v[172:175], v184
	ds_read_b128 v[176:179], v184 offset:512
	ds_read_b128 v[192:195], v184 offset:2048
	ds_read_b128 v[196:199], v184 offset:2560
	s_add_u32 s50, s48, 0xfffc0080
	s_addc_u32 s51, s49, -1
	s_cmp_eq_u32 s93, 12
	s_cselect_b32 s65, s5, s51
	s_cselect_b32 s64, s34, s50
	s_cselect_b32 s51, s27, s92
	s_cselect_b32 s50, s35, s41
	ds_read_b128 v[200:203], v185
	ds_read_b128 v[204:207], v185 offset:512
	ds_read_b128 v[208:211], v185 offset:2048
	ds_read_b128 v[212:215], v185 offset:2560
	ds_read_b128 v[216:219], v185 offset:4096
	ds_read_b128 v[220:223], v185 offset:4608
	ds_read_b128 v[224:227], v185 offset:6144
	ds_read_b128 v[228:231], v185 offset:6656
	s_waitcnt vmcnt(24)
	s_waitcnt lgkmcnt(0)
	s_barrier
	s_setprio 1
	s_waitcnt lgkmcnt(0)
	v_mfma_f32_16x16x32_bf16 v[126:129], v[130:133], v[200:203], 0
	v_mfma_f32_16x16x32_bf16 v[122:125], v[138:141], v[200:203], 0
	v_mfma_f32_16x16x32_bf16 v[110:113], v[130:133], v[208:211], 0
	v_mfma_f32_16x16x32_bf16 v[106:109], v[138:141], v[208:211], 0
	v_mfma_f32_16x16x32_bf16 v[94:97], v[130:133], v[216:219], 0
	v_mfma_f32_16x16x32_bf16 v[90:93], v[138:141], v[216:219], 0
	v_mfma_f32_16x16x32_bf16 v[78:81], v[130:133], v[224:227], 0
	v_mfma_f32_16x16x32_bf16 v[74:77], v[138:141], v[224:227], 0
	v_mfma_f32_16x16x32_bf16 v[126:129], v[134:137], v[204:207], v[126:129]
	v_mfma_f32_16x16x32_bf16 v[122:125], v[142:145], v[204:207], v[122:125]
	v_mfma_f32_16x16x32_bf16 v[110:113], v[134:137], v[212:215], v[110:113]
	v_mfma_f32_16x16x32_bf16 v[106:109], v[142:145], v[212:215], v[106:109]
	v_mfma_f32_16x16x32_bf16 v[94:97], v[134:137], v[220:223], v[94:97]
	v_mfma_f32_16x16x32_bf16 v[90:93], v[142:145], v[220:223], v[90:93]
	v_mfma_f32_16x16x32_bf16 v[78:81], v[134:137], v[228:231], v[78:81]
	v_mfma_f32_16x16x32_bf16 v[74:77], v[142:145], v[228:231], v[74:77]
	s_setprio 0
	s_setprio 1
	v_mfma_f32_16x16x32_bf16 v[118:121], v[172:175], v[200:203], 0
	v_mfma_f32_16x16x32_bf16 v[114:117], v[192:195], v[200:203], 0
	v_mfma_f32_16x16x32_bf16 v[102:105], v[172:175], v[208:211], 0
	v_mfma_f32_16x16x32_bf16 v[98:101], v[192:195], v[208:211], 0
	v_mfma_f32_16x16x32_bf16 v[86:89], v[172:175], v[216:219], 0
	v_mfma_f32_16x16x32_bf16 v[82:85], v[192:195], v[216:219], 0
	v_mfma_f32_16x16x32_bf16 v[70:73], v[172:175], v[224:227], 0
	v_mfma_f32_16x16x32_bf16 v[66:69], v[192:195], v[224:227], 0
	v_mfma_f32_16x16x32_bf16 v[118:121], v[176:179], v[204:207], v[118:121]
	v_mfma_f32_16x16x32_bf16 v[114:117], v[196:199], v[204:207], v[114:117]
	v_mfma_f32_16x16x32_bf16 v[102:105], v[176:179], v[212:215], v[102:105]
	v_mfma_f32_16x16x32_bf16 v[98:101], v[196:199], v[212:215], v[98:101]
	v_mfma_f32_16x16x32_bf16 v[86:89], v[176:179], v[220:223], v[86:89]
	v_mfma_f32_16x16x32_bf16 v[82:85], v[196:199], v[220:223], v[82:85]
	v_mfma_f32_16x16x32_bf16 v[70:73], v[176:179], v[228:231], v[70:73]
	v_mfma_f32_16x16x32_bf16 v[66:69], v[196:199], v[228:231], v[66:69]
	s_setprio 0
	s_barrier
	s_add_i32 s94, s85, s72
	s_mov_b32 m0, s94
	ds_read_b128 v[200:203], v185 offset:16384
	ds_read_b128 v[204:207], v185 offset:16896
	ds_read_b128 v[208:211], v185 offset:18432
	ds_read_b128 v[212:215], v185 offset:18944
	ds_read_b128 v[216:219], v185 offset:20480
	ds_read_b128 v[220:223], v185 offset:20992
	ds_read_b128 v[224:227], v185 offset:22528
	ds_read_b128 v[228:231], v185 offset:23040
	global_load_lds_dwordx4 v148, s[50:51]
	s_add_i32 m0, s94, 0x2000
	s_add_u32 s94, s50, 0x40000
	s_addc_u32 s95, s51, 0
	s_add_i32 s96, s86, s72
	global_load_lds_dwordx4 v152, s[50:51]
	s_mov_b32 m0, s96
	s_nop 0
	global_load_lds_dwordx4 v148, s[94:95]
	s_add_i32 m0, s96, 0x2000
	s_nop 0
	global_load_lds_dwordx4 v152, s[94:95]
	s_mov_b32 m0, s47
	s_nop 0
	global_load_lds_dwordx4 v146, s[64:65]
	s_mov_b32 m0, s73
	s_nop 0
	global_load_lds_dwordx4 v150, s[64:65]
	s_waitcnt vmcnt(24)
	s_waitcnt lgkmcnt(0)
	s_barrier
	s_setprio 1
	s_waitcnt lgkmcnt(0)
	v_mfma_f32_16x16x32_bf16 v[62:65], v[130:133], v[200:203], 0
	v_mfma_f32_16x16x32_bf16 v[58:61], v[138:141], v[200:203], 0
	v_mfma_f32_16x16x32_bf16 v[46:49], v[130:133], v[208:211], 0
	v_mfma_f32_16x16x32_bf16 v[42:45], v[138:141], v[208:211], 0
	v_mfma_f32_16x16x32_bf16 v[30:33], v[130:133], v[216:219], 0
	v_mfma_f32_16x16x32_bf16 v[26:29], v[138:141], v[216:219], 0
	v_mfma_f32_16x16x32_bf16 v[14:17], v[130:133], v[224:227], 0
	v_mfma_f32_16x16x32_bf16 v[10:13], v[138:141], v[224:227], 0
	v_mfma_f32_16x16x32_bf16 v[62:65], v[134:137], v[204:207], v[62:65]
	v_mfma_f32_16x16x32_bf16 v[58:61], v[142:145], v[204:207], v[58:61]
	v_mfma_f32_16x16x32_bf16 v[46:49], v[134:137], v[212:215], v[46:49]
	v_mfma_f32_16x16x32_bf16 v[42:45], v[142:145], v[212:215], v[42:45]
	v_mfma_f32_16x16x32_bf16 v[30:33], v[134:137], v[220:223], v[30:33]
	v_mfma_f32_16x16x32_bf16 v[26:29], v[142:145], v[220:223], v[26:29]
	v_mfma_f32_16x16x32_bf16 v[14:17], v[134:137], v[228:231], v[14:17]
	v_mfma_f32_16x16x32_bf16 v[10:13], v[142:145], v[228:231], v[10:13]
	s_setprio 0
	s_setprio 1
	v_mfma_f32_16x16x32_bf16 v[54:57], v[172:175], v[200:203], 0
	v_mfma_f32_16x16x32_bf16 v[50:53], v[192:195], v[200:203], 0
	v_mfma_f32_16x16x32_bf16 v[38:41], v[172:175], v[208:211], 0
	v_mfma_f32_16x16x32_bf16 v[34:37], v[192:195], v[208:211], 0
	v_mfma_f32_16x16x32_bf16 v[22:25], v[172:175], v[216:219], 0
	v_mfma_f32_16x16x32_bf16 v[18:21], v[192:195], v[216:219], 0
	v_mfma_f32_16x16x32_bf16 v[6:9], v[172:175], v[224:227], 0
	v_mfma_f32_16x16x32_bf16 v[2:5], v[192:195], v[224:227], 0
	v_mfma_f32_16x16x32_bf16 v[54:57], v[176:179], v[204:207], v[54:57]
	v_mfma_f32_16x16x32_bf16 v[50:53], v[196:199], v[204:207], v[50:53]
	v_mfma_f32_16x16x32_bf16 v[38:41], v[176:179], v[212:215], v[38:41]
	v_mfma_f32_16x16x32_bf16 v[34:37], v[196:199], v[212:215], v[34:37]
	v_mfma_f32_16x16x32_bf16 v[22:25], v[176:179], v[220:223], v[22:25]
	v_mfma_f32_16x16x32_bf16 v[18:21], v[196:199], v[220:223], v[18:21]
	v_mfma_f32_16x16x32_bf16 v[6:9], v[176:179], v[228:231], v[6:9]
	v_mfma_f32_16x16x32_bf16 v[2:5], v[196:199], v[228:231], v[2:5]
	s_setprio 0
	s_barrier
; #define PG8_STAGE(bufoff, gbase, voff) do { _Pragma("unroll") for (int _i = 0; _i < 2; ++_i) \
;         __builtin_amdgcn_global_load_lds((const unsigned*)((const char*)(gbase) + (voff)[_i]), (PG8_LAS unsigned*)(lds + (bufoff) + ldsw + _i * 8192), 16, 0, 0); } while (0)
; #define PG8_LDA(dst, b, h) do { _Pragma("unroll") for (int m = 0; m < 4; ++m) _Pragma("unroll") for (int k = 0; k < 2; ++k) dst[m][k] = *(const PG8_LAS bf16x8*)(lds + PG8_SA(b, h) + aoff + m * 2048 + k * 1024); } while (0)
; #define PG8_LDB(dst, b, h) do { _Pragma("unroll") for (int n = 0; n < 2; ++n) _Pragma("unroll") for (int k = 0; k < 2; ++k) dst[n][k] = *(const PG8_LAS bf16x8*)(lds + PG8_SB(b, h) + boff + n * 2048 + k * 1024); } while (0)
; #define PG8_MMA(ai, bj, At, Bt) do { __builtin_amdgcn_s_setprio(1); _Pragma("unroll") for (int m = 0; m < 4; ++m) _Pragma("unroll") for (int n = 0; n < 2; ++n) _Pragma("unroll") for (int k = 0; k < 2; ++k) \
;         acc[ai][bj][m][n] = __builtin_amdgcn_mfma_f32_16x16x32_bf16(Bt[n][k], At[m][k], acc[ai][bj][m][n], 0, 0, 0); __builtin_amdgcn_s_setprio(0); } while (0)
; #define PG8_WAIT_V(n) asm volatile("s_waitcnt vmcnt(" #n ")" ::: "memory")
; #define PG8_WAIT_L(n) asm volatile("s_waitcnt lgkmcnt(" #n ")" ::: "memory")
; #define PG8_BAR __builtin_amdgcn_s_barrier()
; #define PG8_SCHED __builtin_amdgcn_sched_barrier(0)
; template <class Epi, class Sched, bool ALIGN_EPI = false, bool SP2 = false>
; __device__ __forceinline__ void gemm_phase(PG8_LAS unsigned char* lds, const Gemm g, const Sched& S, const Epi& E) {
;     ...
;             PG8_LDB(B0, 1, 0); PG8_LDB(B1, 1, 1); PG8_SCHED; PG8_LDA(At, 1, 0); PG8_STAGE(PG8_SA(0, 1), a2 + hstep, voffA);
;             PG8_WAIT_V(8); PG8_WAIT_L(0); PG8_BAR; PG8_MMA(0, 0, At, B0); PG8_MMA(0, 1, At, B1); PG8_BAR; PG8_SCHED;
;             PG8_LDA(At, 1, 1); PG8_STAGE(PG8_SB(1, 0), b3, voffB); PG8_STAGE(PG8_SB(1, 1), b3 + hstep, voffB); PG8_STAGE(PG8_SA(1, 0), a3, voffA);
;             PG8_WAIT_V(8); PG8_WAIT_L(0); PG8_BAR; PG8_MMA(1, 0, At, B0); PG8_MMA(1, 1, At, B1); PG8_BAR; PG8_SCHED;
	s_add_i32 s94, 0, 0x18000
	s_add_i32 s95, 0, 0x1c000
	v_add_u32_e32 v142, s94, v181
	v_add_u32_e32 v154, s95, v181
	ds_read_b128 v[130:133], v142
	ds_read_b128 v[134:137], v142 offset:512
	ds_read_b128 v[138:141], v142 offset:2048
	ds_read_b128 v[142:145], v142 offset:2560
	ds_read_b128 v[172:175], v154
	ds_read_b128 v[176:179], v154 offset:512
	ds_read_b128 v[192:195], v154 offset:2048
	ds_read_b128 v[196:199], v154 offset:2560
	s_add_u32 s64, s64, 0x40000
	s_addc_u32 s65, s65, 0
	s_mov_b32 m0, s74
	ds_read_b128 v[200:203], v185 offset:32768
	ds_read_b128 v[204:207], v185 offset:33280
	ds_read_b128 v[208:211], v185 offset:34816
	ds_read_b128 v[212:215], v185 offset:35328
	ds_read_b128 v[216:219], v185 offset:36864
	ds_read_b128 v[220:223], v185 offset:37376
	ds_read_b128 v[224:227], v185 offset:38912
	ds_read_b128 v[228:231], v185 offset:39424
	global_load_lds_dwordx4 v146, s[64:65]
	s_mov_b32 m0, s75
	s_nop 0
	global_load_lds_dwordx4 v150, s[64:65]
	s_waitcnt vmcnt(24)
	s_waitcnt lgkmcnt(0)
	s_barrier
	s_setprio 1
	s_waitcnt lgkmcnt(0)
	v_mfma_f32_16x16x32_bf16 v[126:129], v[130:133], v[200:203], v[126:129]
	v_mfma_f32_16x16x32_bf16 v[122:125], v[138:141], v[200:203], v[122:125]
	v_mfma_f32_16x16x32_bf16 v[110:113], v[130:133], v[208:211], v[110:113]
	v_mfma_f32_16x16x32_bf16 v[106:109], v[138:141], v[208:211], v[106:109]
	v_mfma_f32_16x16x32_bf16 v[94:97], v[130:133], v[216:219], v[94:97]
	v_mfma_f32_16x16x32_bf16 v[90:93], v[138:141], v[216:219], v[90:93]
	v_mfma_f32_16x16x32_bf16 v[78:81], v[130:133], v[224:227], v[78:81]
	v_mfma_f32_16x16x32_bf16 v[74:77], v[138:141], v[224:227], v[74:77]
	v_mfma_f32_16x16x32_bf16 v[126:129], v[134:137], v[204:207], v[126:129]
	v_mfma_f32_16x16x32_bf16 v[122:125], v[142:145], v[204:207], v[122:125]
	v_mfma_f32_16x16x32_bf16 v[110:113], v[134:137], v[212:215], v[110:113]
	v_mfma_f32_16x16x32_bf16 v[106:109], v[142:145], v[212:215], v[106:109]
	v_mfma_f32_16x16x32_bf16 v[94:97], v[134:137], v[220:223], v[94:97]
	v_mfma_f32_16x16x32_bf16 v[90:93], v[142:145], v[220:223], v[90:93]
	v_mfma_f32_16x16x32_bf16 v[78:81], v[134:137], v[228:231], v[78:81]
	v_mfma_f32_16x16x32_bf16 v[74:77], v[142:145], v[228:231], v[74:77]
	s_setprio 0
	s_setprio 1
	v_mfma_f32_16x16x32_bf16 v[118:121], v[172:175], v[200:203], v[118:121]
	v_mfma_f32_16x16x32_bf16 v[114:117], v[192:195], v[200:203], v[114:117]
	v_mfma_f32_16x16x32_bf16 v[102:105], v[172:175], v[208:211], v[102:105]
	v_mfma_f32_16x16x32_bf16 v[98:101], v[192:195], v[208:211], v[98:101]
	v_mfma_f32_16x16x32_bf16 v[86:89], v[172:175], v[216:219], v[86:89]
	v_mfma_f32_16x16x32_bf16 v[82:85], v[192:195], v[216:219], v[82:85]
	v_mfma_f32_16x16x32_bf16 v[70:73], v[172:175], v[224:227], v[70:73]
	v_mfma_f32_16x16x32_bf16 v[66:69], v[192:195], v[224:227], v[66:69]
	v_mfma_f32_16x16x32_bf16 v[118:121], v[176:179], v[204:207], v[118:121]
	v_mfma_f32_16x16x32_bf16 v[114:117], v[196:199], v[204:207], v[114:117]
	v_mfma_f32_16x16x32_bf16 v[102:105], v[176:179], v[212:215], v[102:105]
	v_mfma_f32_16x16x32_bf16 v[98:101], v[196:199], v[212:215], v[98:101]
	v_mfma_f32_16x16x32_bf16 v[86:89], v[176:179], v[220:223], v[86:89]
	v_mfma_f32_16x16x32_bf16 v[82:85], v[196:199], v[220:223], v[82:85]
	v_mfma_f32_16x16x32_bf16 v[70:73], v[176:179], v[228:231], v[70:73]
	v_mfma_f32_16x16x32_bf16 v[66:69], v[196:199], v[228:231], v[66:69]
	s_setprio 0
	s_barrier
	s_add_i32 s96, s94, s72
	s_add_u32 s12, s50, 0x80
	s_addc_u32 s13, s51, 0
	s_mov_b32 m0, s96
	ds_read_b128 v[200:203], v185 offset:49152
	ds_read_b128 v[204:207], v185 offset:49664
	ds_read_b128 v[208:211], v185 offset:51200
	ds_read_b128 v[212:215], v185 offset:51712
	ds_read_b128 v[216:219], v185 offset:53248
	ds_read_b128 v[220:223], v185 offset:53760
	ds_read_b128 v[224:227], v185 offset:55296
	ds_read_b128 v[228:231], v185 offset:55808
	global_load_lds_dwordx4 v148, s[12:13]
	s_add_i32 m0, s96, 0x2000
	s_add_u32 s50, s50, 0x40080
	s_addc_u32 s51, s51, 0
	s_add_i32 s96, s95, s72
	global_load_lds_dwordx4 v152, s[12:13]
	s_mov_b32 m0, s96
	s_nop 0
	global_load_lds_dwordx4 v148, s[50:51]
	s_add_i32 m0, s96, 0x2000
	s_nop 0
	global_load_lds_dwordx4 v152, s[50:51]
	s_add_u32 s64, s64, 0xfffc0080
	s_addc_u32 s65, s65, -1
	s_mov_b32 m0, s82
	s_nop 0
	global_load_lds_dwordx4 v146, s[64:65]
	s_mov_b32 m0, s83
	s_nop 0
	global_load_lds_dwordx4 v150, s[64:65]
	s_waitcnt vmcnt(8)
	s_waitcnt lgkmcnt(0)
	s_barrier
	s_setprio 1
	s_waitcnt lgkmcnt(0)
	v_mfma_f32_16x16x32_bf16 v[62:65], v[130:133], v[200:203], v[62:65]
	v_mfma_f32_16x16x32_bf16 v[58:61], v[138:141], v[200:203], v[58:61]
	v_mfma_f32_16x16x32_bf16 v[46:49], v[130:133], v[208:211], v[46:49]
	v_mfma_f32_16x16x32_bf16 v[42:45], v[138:141], v[208:211], v[42:45]
	v_mfma_f32_16x16x32_bf16 v[30:33], v[130:133], v[216:219], v[30:33]
	v_mfma_f32_16x16x32_bf16 v[26:29], v[138:141], v[216:219], v[26:29]
	v_mfma_f32_16x16x32_bf16 v[14:17], v[130:133], v[224:227], v[14:17]
	v_mfma_f32_16x16x32_bf16 v[10:13], v[138:141], v[224:227], v[10:13]
	v_mfma_f32_16x16x32_bf16 v[62:65], v[134:137], v[204:207], v[62:65]
	v_mfma_f32_16x16x32_bf16 v[58:61], v[142:145], v[204:207], v[58:61]
	v_mfma_f32_16x16x32_bf16 v[46:49], v[134:137], v[212:215], v[46:49]
	v_mfma_f32_16x16x32_bf16 v[42:45], v[142:145], v[212:215], v[42:45]
	v_mfma_f32_16x16x32_bf16 v[30:33], v[134:137], v[220:223], v[30:33]
	v_mfma_f32_16x16x32_bf16 v[26:29], v[142:145], v[220:223], v[26:29]
	v_mfma_f32_16x16x32_bf16 v[14:17], v[134:137], v[228:231], v[14:17]
	v_mfma_f32_16x16x32_bf16 v[10:13], v[142:145], v[228:231], v[10:13]
	s_setprio 0
	s_setprio 1
	v_mfma_f32_16x16x32_bf16 v[54:57], v[172:175], v[200:203], v[54:57]
	v_mfma_f32_16x16x32_bf16 v[50:53], v[192:195], v[200:203], v[50:53]
	v_mfma_f32_16x16x32_bf16 v[38:41], v[172:175], v[208:211], v[38:41]
	v_mfma_f32_16x16x32_bf16 v[34:37], v[192:195], v[208:211], v[34:37]
	v_mfma_f32_16x16x32_bf16 v[22:25], v[172:175], v[216:219], v[22:25]
	v_mfma_f32_16x16x32_bf16 v[18:21], v[192:195], v[216:219], v[18:21]
	v_mfma_f32_16x16x32_bf16 v[6:9], v[172:175], v[224:227], v[6:9]
	v_mfma_f32_16x16x32_bf16 v[2:5], v[192:195], v[224:227], v[2:5]
	v_mfma_f32_16x16x32_bf16 v[54:57], v[176:179], v[204:207], v[54:57]
	v_mfma_f32_16x16x32_bf16 v[50:53], v[196:199], v[204:207], v[50:53]
	v_mfma_f32_16x16x32_bf16 v[38:41], v[176:179], v[212:215], v[38:41]
	v_mfma_f32_16x16x32_bf16 v[34:37], v[196:199], v[212:215], v[34:37]
	v_mfma_f32_16x16x32_bf16 v[22:25], v[176:179], v[220:223], v[22:25]
	v_mfma_f32_16x16x32_bf16 v[18:21], v[196:199], v[220:223], v[18:21]
	v_mfma_f32_16x16x32_bf16 v[6:9], v[176:179], v[228:231], v[6:9]
	v_mfma_f32_16x16x32_bf16 v[2:5], v[196:199], v[228:231], v[2:5]
	s_setprio 0
	s_barrier
	s_add_i32 s93, s93, 2
	s_add_u32 s48, s48, 0x100
	s_addc_u32 s49, s49, 0
	s_add_u32 s41, s41, 0x100
	s_addc_u32 s92, s92, 0
	s_branch .LBB0_162

; #define PG8_STAGE(bufoff, gbase, voff) do { _Pragma("unroll") for (int _i = 0; _i < 2; ++_i) \
;         __builtin_amdgcn_global_load_lds((const unsigned*)((const char*)(gbase) + (voff)[_i]), (PG8_LAS unsigned*)(lds + (bufoff) + ldsw + _i * 8192), 16, 0, 0); } while (0)
; #define PG8_WAIT_V(n) asm volatile("s_waitcnt vmcnt(" #n ")" ::: "memory")
; #define PG8_BAR __builtin_amdgcn_s_barrier()
; template <class Epi, class Sched, bool ALIGN_EPI = false, bool SP2 = false>
; __device__ __forceinline__ void gemm_phase(PG8_LAS unsigned char* lds, const Gemm g, const Sched& S, const Epi& E) {
;     const int tid = threadIdx.x, wid = __builtin_amdgcn_readfirstlane(tid >> 6), lane = tid & 63, wr = wid >> 2, wc = wid & 3, fr = lane & 15, fq = lane >> 4;
;     const int K = g.K, nt = K / BK;
;     unsigned voffA[2], voffB[2];
; #pragma unroll
;     for (int i = 0; i < 2; ++i) { int R, C; stage_rc(tid * 16 + i * 8192, R, C); const int Rb = Epi::PERM ? ((R & ~31) + perm32(R & 31)) : R;
;         voffA[i] = (unsigned)(R * K + C) * 2u; voffB[i] = (unsigned)(Rb * K + C) * 2u; }
;     const size_t kstep = (size_t)(BK * 2);
;     const size_t hstep = (size_t)HALF * K * 2;
;     const size_t tstep = 2 * hstep;
;     const unsigned ldsw = (unsigned)wid * 1024u;
;     const int aoff = lds_byte(wr * 64 + fr, fq * 8), boff = lds_byte(wc * 32 + fr, fq * 8);
;     ...
;     if constexpr (SP2) {
;         PG8_STAGE(PG8_SB(0, 0), cB, voffB); PG8_STAGE(PG8_SB(0, 1), cB + hstep, voffB); PG8_STAGE(PG8_SA(0, 0), cA, voffA); PG8_STAGE(PG8_SA(0, 1), cA + hstep, voffA);
;         if (wr == 1) PG8_BAR;
;         PG8_WAIT_V(2); PG8_BAR;
;         PG8_STAGE(PG8_SB(1, 0), cB + kstep, voffB); PG8_STAGE(PG8_SA(1, 0), cA + kstep, voffA); PG8_STAGE(PG8_SB(1, 1), cB + hstep + kstep, voffB);
;         PG8_WAIT_V(6); PG8_BAR;
;     } else {
;         PG8_STAGE(PG8_SB(0, 0), cB, voffB); PG8_STAGE(PG8_SA(0, 0), cA, voffA); PG8_STAGE(PG8_SB(0, 1), cB + hstep, voffB); PG8_STAGE(PG8_SA(0, 1), cA + hstep, voffA);
;         if (wr == 1) PG8_BAR;
;         PG8_WAIT_V(4); PG8_BAR;
;         PG8_STAGE(PG8_SB(1, 0), cB + kstep, voffB); PG8_STAGE(PG8_SA(1, 0), cA + kstep, voffA); PG8_STAGE(PG8_SB(1, 1), cB + hstep + kstep, voffB);
.LBB0_447:
	s_cmp_gt_i32 s28, 5
	s_cselect_b64 s[4:5], -1, 0
	s_xor_b64 s[0:1], s[0:1], -1
	s_or_b64 s[0:1], s[4:5], s[0:1]
	s_and_b64 vcc, exec, s[0:1]
	s_cbranch_vccnz .LBB0_464
	s_cmpk_gt_i32 s2, 0x4ff
	v_readfirstlane_b32 s1, v0
	s_cbranch_scc1 .LBB0_464
	v_bfe_u32 v1, v0, 2, 3
	v_bfe_u32 v2, v0, 5, 1
	v_bfe_u32 v3, v0, 4, 1
	v_and_b32_e32 v4, 3, v0
	v_lshlrev_b32_e32 v3, 1, v3
	v_xor_b32_e32 v4, v4, v3
	v_lshlrev_b32_e32 v4, 4, v4
	v_lshl_or_b32 v4, v2, 6, v4
	v_lshrrev_b32_e32 v5, 6, v0
	v_lshl_or_b32 v6, v5, 3, v1
	v_lshl_or_b32 v251, v6, 11, v4
	v_and_b32_e32 v6, 1, v5
	v_bfe_u32 v7, v5, 1, 1
	v_lshrrev_b32_e32 v5, 2, v5
	v_lshlrev_b32_e32 v5, 5, v5
	v_lshl_or_b32 v5, v6, 4, v5
	v_lshl_or_b32 v5, v7, 2, v5
	v_bfe_u32 v6, v1, 2, 1
	v_lshl_or_b32 v5, v6, 3, v5
	v_and_b32_e32 v6, 3, v1
	v_or_b32_e32 v5, v5, v6
	v_lshl_or_b32 v252, v5, 11, v4
	v_bfe_u32 v1, v0, 4, 2
	v_bfe_u32 v2, v0, 2, 1
	v_lshlrev_b32_e32 v2, 1, v2
	v_xor_b32_e32 v1, v1, v2
	v_lshlrev_b32_e32 v1, 4, v1
	v_and_b32_e32 v2, 7, v0
	v_lshl_or_b32 v1, v2, 6, v1
	v_bfe_u32 v2, v0, 3, 1
	v_lshl_or_b32 v253, v2, 10, v1
	v_lshrrev_b32_e32 v4, 1, v0
	s_waitcnt vmcnt(0)
	v_and_b32_e32 v12, 24, v4
	v_lshrrev_b32_e32 v4, 5, v0
	s_add_u32 s33, s22, 0x2000000
	v_lshlrev_b32_e32 v2, 4, v0
	v_and_b32_e32 v1, 32, v0
	v_and_b32_e32 v4, 4, v4
	v_bfe_u32 v5, v0, 2, 2
	s_addc_u32 s42, s23, 0
	v_bfe_u32 v11, v0, 2, 4
	v_bitop3_b32 v1, v2, v1, 48 bitop3:0x6c
	v_and_b32_e32 v10, 64, v0
	v_or3_b32 v4, v4, v5, v12
	v_lshrrev_b32_e32 v5, 3, v0
	v_or_b32_e32 v13, 0x2000, v2
	s_add_u32 s43, s22, 0x1800000
	v_or_b32_e32 v3, v1, v10
	v_and_or_b32 v6, v5, 48, v11
	v_and_or_b32 v5, v5, 32, v4
	v_lshrrev_b32_e32 v2, 7, v13
	s_movk_i32 s0, 0x70
	s_addc_u32 s44, s23, 0
	v_mov_b32_e32 v146, v252
	v_and_or_b32 v5, v2, s0, v11
	s_movk_i32 s0, 0x60
	s_ashr_i32 s46, s2, 31
	v_and_or_b32 v2, v2, s0, v4
	s_lshr_b32 s0, s46, 29
	s_add_i32 s0, s2, s0
	s_lshr_b32 s6, s1, 6
	s_ashr_i32 s4, s0, 3
	s_and_b32 s0, s0, -8
	s_lshr_b32 s8, s1, 8
	s_lshl_b32 s45, s6, 10
	s_sub_i32 s0, s2, s0
	s_cmp_lt_i32 s0, 0
	s_movk_i32 s47, 0xa1
	s_cselect_b32 s5, s47, 0xa0
	s_mul_i32 s0, s0, s5
	s_add_i32 s0, s0, s4
	s_ashr_i32 s4, s0, 31
	s_lshr_b32 s4, s4, 28
	s_add_i32 s4, s0, s4
	s_ashr_i32 s5, s4, 4
	s_and_b32 s4, s4, 0xfff0
	s_sub_i32 s4, s0, s4
	s_bfe_i32 s0, s4, 0x80000
	s_bfe_u32 s0, s0, 0x2000d
	s_add_i32 s7, s4, s0
	s_bfe_i32 s0, s7, 0x80000
	s_and_b32 s7, s7, 0xfc
	s_sub_i32 s4, s4, s7
	s_lshl_b32 s5, s5, 2
	s_sext_i32_i16 s0, s0
	s_sext_i32_i8 s4, s4
	s_lshr_b32 s0, s0, 2
	s_add_i32 s30, s5, s4
	s_ashr_i32 s31, s30, 31
	s_bfe_i64 s[10:11], s[0:1], 0x100000
	s_lshl_b64 s[4:5], s[30:31], 19
	s_lshl_b64 s[10:11], s[10:11], 19
	s_add_u32 s40, s43, s10
	s_addc_u32 s41, s44, s11
	s_add_i32 s31, s45, 0
	s_add_i32 m0, s31, 0x10000
	v_add_u32_e32 v150, 0x20000, v252
	global_load_lds_dwordx4 v146, s[40:41]
	s_add_i32 m0, s31, 0x12000
	s_add_u32 s10, s40, 0x40000
	global_load_lds_dwordx4 v150, s[40:41]
	s_addc_u32 s11, s41, 0
	s_add_i32 m0, s31, 0x14000
	v_mov_b32_e32 v144, v251
	global_load_lds_dwordx4 v146, s[10:11]
	s_add_i32 m0, s31, 0x16000
	s_add_u32 s34, s33, s4
	s_addc_u32 s35, s42, s5
	s_add_i32 s48, s31, 0x2000
	global_load_lds_dwordx4 v150, s[10:11]
	s_mov_b32 m0, s31
	s_add_u32 s4, s34, 0x40000
	v_add_u32_e32 v148, 0x20000, v251
	global_load_lds_dwordx4 v144, s[34:35]
	s_mov_b32 m0, s48
	s_addc_u32 s5, s35, 0
	s_add_i32 s49, s31, 0x4000
	global_load_lds_dwordx4 v148, s[34:35]
	s_mov_b32 m0, s49
	s_add_i32 s50, s31, 0x6000
	global_load_lds_dwordx4 v144, s[4:5]
	s_mov_b32 m0, s50
	v_mov_b32_e32 v147, 0
	global_load_lds_dwordx4 v148, s[4:5]
	v_mov_b32_e32 v151, v147
	v_mov_b32_e32 v145, v147
	v_mov_b32_e32 v149, v147
	s_cmp_eq_u32 s8, 1
	s_mov_b32 s51, 0
	v_lshl_add_u64 v[8:9], s[40:41], 0, v[146:147]
	v_lshl_add_u64 v[6:7], s[40:41], 0, v[150:151]
	s_mov_b32 s52, 0x12000
	v_lshl_add_u64 v[2:3], s[34:35], 0, v[144:145]
	s_cselect_b64 s[4:5], -1, 0
	s_cmp_lg_u32 s8, 1
	v_lshl_add_u64 v[4:5], s[34:35], 0, v[148:149]
	s_cbranch_scc1 .LBB0_451
	s_barrier
.LBB0_451:
	s_ashr_i32 s53, s3, 31
	s_add_u32 s54, s38, 0xf0000000
	s_addc_u32 s55, s39, -1
	s_lshl_b32 s6, s6, 5
	s_and_b32 s12, s6, 0x60
	s_mov_b64 s[6:7], 0x80
	s_add_i32 m0, s31, 0x18000
	v_lshl_add_u64 v[8:9], v[8:9], 0, s[6:7]
	s_lshl_b32 s9, s8, 13
	s_lshl_b32 s13, s12, 7
	s_waitcnt vmcnt(2)
	s_barrier
	global_load_lds_dwordx4 v[8:9], off
	v_lshl_add_u64 v[6:7], v[6:7], 0, s[6:7]
	s_add_i32 m0, s31, 0x1a000
	s_add_i32 s56, s31, 0x8000
	s_add_i32 s57, s31, 0xa000
	global_load_lds_dwordx4 v[6:7], off
	v_lshl_add_u64 v[2:3], v[2:3], 0, s[6:7]
	s_mov_b32 m0, s56
	s_add_u32 s10, s40, 0x40080
	global_load_lds_dwordx4 v[2:3], off
	v_lshl_add_u64 v[2:3], v[4:5], 0, s[6:7]
	s_mov_b32 m0, s57
	s_addc_u32 s11, s41, 0
	global_load_lds_dwordx4 v[2:3], off
	s_add_i32 m0, s31, 0x1c000
	v_lshl_add_u64 v[2:3], s[10:11], 0, v[146:147]
	global_load_lds_dwordx4 v[2:3], off
	v_lshl_add_u64 v[2:3], s[10:11], 0, v[150:151]
	s_add_i32 m0, s31, 0x1e000
	s_sext_i32_i8 s60, s0
	global_load_lds_dwordx4 v[2:3], off
	v_and_b32_e32 v2, 15, v0
	v_lshlrev_b32_e32 v3, 1, v12
	v_lshlrev_b32_e32 v4, 6, v0
	s_movk_i32 s0, 0x3c0
	v_lshlrev_b32_e32 v5, 2, v0
	v_lshlrev_b32_e32 v0, 8, v0
	v_and_or_b32 v4, v4, s0, v3
	v_lshl_or_b32 v166, s8, 6, v2
	v_lshl_or_b32 v2, v2, 6, v3
	v_and_b32_e32 v0, 0x18000, v0
	v_lshlrev_b32_e32 v3, 11, v11
	v_or3_b32 v0, v1, v0, v3
	v_mov_b32_e32 v152, v251
	v_lshlrev_b32_e32 v0, 4, v13
	v_and_b32_e32 v5, 32, v5
	s_waitcnt vmcnt(6)
	s_cmpk_lt_u32 s1, 0x100
	v_and_b32_e32 v0, 0x38000, v0
	v_or_b32_e32 v2, s9, v253
	v_or_b32_e32 v167, s13, v253
	s_cselect_b64 s[8:9], -1, 0
	v_or3_b32 v0, v1, v0, v3
	s_add_i32 s58, 0, 0x10000
	s_add_i32 s59, 0, 0x14000
	v_or_b32_e32 v168, s12, v12
	v_mov_b32_e32 v153, v147
	v_add_u32_e32 v154, 0x20000, v251
	v_mov_b32_e32 v155, v147
	v_mov_b64_e32 v[156:157], 0x500
	v_mov_b64_e32 v[158:159], 0x4ff
	v_add_u32_e32 v169, s58, v167
	v_add_u32_e32 v170, s59, v167
	v_add_u32_e32 v171, 0, v2
	s_mov_b64 s[10:11], 0x12000
	s_mov_b64 s[12:13], 0x80000
	s_mov_b64 s[14:15], 0x90000
	s_mov_b64 s[16:17], 0xa0000
	s_mov_b64 s[18:19], 0xb0000
	s_barrier
	s_branch .LBB0_454

; #define PG8_STAGE(bufoff, gbase, voff) do { _Pragma("unroll") for (int _i = 0; _i < 2; ++_i) \
;         __builtin_amdgcn_global_load_lds((const unsigned*)((const char*)(gbase) + (voff)[_i]), (PG8_LAS unsigned*)(lds + (bufoff) + ldsw + _i * 8192), 16, 0, 0); } while (0)
; #define PG8_LDA(dst, b, h) do { _Pragma("unroll") for (int m = 0; m < 4; ++m) _Pragma("unroll") for (int k = 0; k < 2; ++k) dst[m][k] = *(const PG8_LAS bf16x8*)(lds + PG8_SA(b, h) + aoff + m * 2048 + k * 1024); } while (0)
; #define PG8_LDB(dst, b, h) do { _Pragma("unroll") for (int n = 0; n < 2; ++n) _Pragma("unroll") for (int k = 0; k < 2; ++k) dst[n][k] = *(const PG8_LAS bf16x8*)(lds + PG8_SB(b, h) + boff + n * 2048 + k * 1024); } while (0)
; #define PG8_MMA(ai, bj, At, Bt) do { __builtin_amdgcn_s_setprio(1); _Pragma("unroll") for (int m = 0; m < 4; ++m) _Pragma("unroll") for (int n = 0; n < 2; ++n) _Pragma("unroll") for (int k = 0; k < 2; ++k) \
;         acc[ai][bj][m][n] = __builtin_amdgcn_mfma_f32_16x16x32_bf16(Bt[n][k], At[m][k], acc[ai][bj][m][n], 0, 0, 0); __builtin_amdgcn_s_setprio(0); } while (0)
; #define PG8_WAIT_V(n) asm volatile("s_waitcnt vmcnt(" #n ")" ::: "memory")
; #define PG8_WAIT_L(n) asm volatile("s_waitcnt lgkmcnt(" #n ")" ::: "memory")
; #define PG8_BAR __builtin_amdgcn_s_barrier()
; #define PG8_SCHED __builtin_amdgcn_sched_barrier(0)
; template <class Epi, class Sched, bool ALIGN_EPI = false, bool SP2 = false>
; __device__ __forceinline__ void gemm_phase(PG8_LAS unsigned char* lds, const Gemm g, const Sched& S, const Epi& E) {
;     ...
;             PG8_LDB(B0, 0, 0); PG8_LDB(B1, 0, 1); PG8_SCHED; PG8_LDA(At, 0, 0); PG8_STAGE(PG8_SA(1, 1), a1 + hstep, voffA);
;             PG8_WAIT_V(8); PG8_WAIT_L(0); PG8_BAR; PG8_MMA(0, 0, At, B0); PG8_MMA(0, 1, At, B1); PG8_BAR; PG8_SCHED;
;             PG8_LDA(At, 0, 1); PG8_STAGE(PG8_SB(0, 0), b2, voffB); PG8_STAGE(PG8_SB(0, 1), b2 + hstep, voffB); PG8_STAGE(PG8_SA(0, 0), a2, voffA);
;             PG8_WAIT_V(8); PG8_WAIT_L(0); PG8_BAR; PG8_MMA(1, 0, At, B0); PG8_MMA(1, 1, At, B1); PG8_BAR; PG8_SCHED;
.LBB0_457:
	ds_read_b128 v[128:131], v169
	ds_read_b128 v[132:135], v169 offset:512
	ds_read_b128 v[136:139], v169 offset:2048
	ds_read_b128 v[140:143], v169 offset:2560
	ds_read_b128 v[160:163], v170
	ds_read_b128 v[172:175], v170 offset:512
	ds_read_b128 v[176:179], v170 offset:2048
	ds_read_b128 v[180:183], v170 offset:2560
	s_add_u32 s38, s34, 0xfffc0080
	s_addc_u32 s39, s35, -1
	s_cmp_eq_u32 s65, 12
	s_cselect_b32 s41, s25, s39
	s_cselect_b32 s40, s61, s38
	s_cselect_b32 s39, s21, s64
	s_cselect_b32 s38, s62, s63
	v_lshl_add_u64 v[164:165], s[34:35], 0, v[152:153]
	s_add_i32 m0, s31, 0xc000
	ds_read_b128 v[184:187], v171
	ds_read_b128 v[188:191], v171 offset:512
	ds_read_b128 v[192:195], v171 offset:2048
	ds_read_b128 v[196:199], v171 offset:2560
	ds_read_b128 v[200:203], v171 offset:4096
	ds_read_b128 v[204:207], v171 offset:4608
	ds_read_b128 v[208:211], v171 offset:6144
	ds_read_b128 v[212:215], v171 offset:6656
	global_load_lds_dwordx4 v[164:165], off
	v_lshl_add_u64 v[164:165], s[34:35], 0, v[154:155]
	s_add_i32 m0, s31, 0xe000
	s_nop 0
	global_load_lds_dwordx4 v[164:165], off
	s_waitcnt vmcnt(8)
	s_waitcnt lgkmcnt(0)
	s_barrier
	s_setprio 1
	s_waitcnt lgkmcnt(0)
	v_mfma_f32_16x16x32_bf16 v[124:127], v[128:131], v[184:187], v[124:127]
	v_mfma_f32_16x16x32_bf16 v[120:123], v[136:139], v[184:187], v[120:123]
	v_mfma_f32_16x16x32_bf16 v[116:119], v[128:131], v[192:195], v[116:119]
	v_mfma_f32_16x16x32_bf16 v[112:115], v[136:139], v[192:195], v[112:115]
	v_mfma_f32_16x16x32_bf16 v[96:99], v[128:131], v[200:203], v[96:99]
	v_mfma_f32_16x16x32_bf16 v[88:91], v[136:139], v[200:203], v[88:91]
	v_mfma_f32_16x16x32_bf16 v[84:87], v[128:131], v[208:211], v[84:87]
	v_mfma_f32_16x16x32_bf16 v[76:79], v[136:139], v[208:211], v[76:79]
	v_mfma_f32_16x16x32_bf16 v[124:127], v[132:135], v[188:191], v[124:127]
	v_mfma_f32_16x16x32_bf16 v[120:123], v[140:143], v[188:191], v[120:123]
	v_mfma_f32_16x16x32_bf16 v[116:119], v[132:135], v[196:199], v[116:119]
	v_mfma_f32_16x16x32_bf16 v[112:115], v[140:143], v[196:199], v[112:115]
	v_mfma_f32_16x16x32_bf16 v[96:99], v[132:135], v[204:207], v[96:99]
	v_mfma_f32_16x16x32_bf16 v[88:91], v[140:143], v[204:207], v[88:91]
	v_mfma_f32_16x16x32_bf16 v[84:87], v[132:135], v[212:215], v[84:87]
	v_mfma_f32_16x16x32_bf16 v[76:79], v[140:143], v[212:215], v[76:79]
	s_setprio 0
	s_setprio 1
	v_mfma_f32_16x16x32_bf16 v[108:111], v[160:163], v[184:187], v[108:111]
	v_mfma_f32_16x16x32_bf16 v[104:107], v[176:179], v[184:187], v[104:107]
	v_mfma_f32_16x16x32_bf16 v[100:103], v[160:163], v[192:195], v[100:103]
	v_mfma_f32_16x16x32_bf16 v[92:95], v[176:179], v[192:195], v[92:95]
	v_mfma_f32_16x16x32_bf16 v[80:83], v[160:163], v[200:203], v[80:83]
	v_mfma_f32_16x16x32_bf16 v[72:75], v[176:179], v[200:203], v[72:75]
	v_mfma_f32_16x16x32_bf16 v[68:71], v[160:163], v[208:211], v[68:71]
	v_mfma_f32_16x16x32_bf16 v[64:67], v[176:179], v[208:211], v[64:67]
	v_mfma_f32_16x16x32_bf16 v[108:111], v[172:175], v[188:191], v[108:111]
	v_mfma_f32_16x16x32_bf16 v[104:107], v[180:183], v[188:191], v[104:107]
	v_mfma_f32_16x16x32_bf16 v[100:103], v[172:175], v[196:199], v[100:103]
	v_mfma_f32_16x16x32_bf16 v[92:95], v[180:183], v[196:199], v[92:95]
	v_mfma_f32_16x16x32_bf16 v[80:83], v[172:175], v[204:207], v[80:83]
	v_mfma_f32_16x16x32_bf16 v[72:75], v[180:183], v[204:207], v[72:75]
	v_mfma_f32_16x16x32_bf16 v[68:71], v[172:175], v[212:215], v[68:71]
	v_mfma_f32_16x16x32_bf16 v[64:67], v[180:183], v[212:215], v[64:67]
	s_setprio 0
	s_barrier
	s_add_i32 s68, s58, s45
	v_lshl_add_u64 v[164:165], s[38:39], 0, v[146:147]
	s_mov_b32 m0, s68
	ds_read_b128 v[184:187], v171 offset:16384
	ds_read_b128 v[188:191], v171 offset:16896
	ds_read_b128 v[192:195], v171 offset:18432
	ds_read_b128 v[196:199], v171 offset:18944
	ds_read_b128 v[200:203], v171 offset:20480
	ds_read_b128 v[204:207], v171 offset:20992
	ds_read_b128 v[208:211], v171 offset:22528
	ds_read_b128 v[212:215], v171 offset:23040
	global_load_lds_dwordx4 v[164:165], off
	s_add_i32 m0, s68, 0x2000
	s_add_u32 s68, s38, 0x40000
	v_lshl_add_u64 v[216:217], s[38:39], 0, v[150:151]
	s_addc_u32 s69, s39, 0
	s_add_i32 s70, s59, s45
	global_load_lds_dwordx4 v[216:217], off
	v_lshl_add_u64 v[218:219], s[68:69], 0, v[146:147]
	s_mov_b32 m0, s70
	v_lshl_add_u64 v[220:221], s[40:41], 0, v[148:149]
	global_load_lds_dwordx4 v[218:219], off
	v_lshl_add_u64 v[218:219], s[68:69], 0, v[150:151]
	s_add_i32 m0, s70, 0x2000
	s_nop 0
	global_load_lds_dwordx4 v[218:219], off
	v_lshl_add_u64 v[218:219], s[40:41], 0, v[144:145]
	s_mov_b32 m0, s31
	s_nop 0
	global_load_lds_dwordx4 v[218:219], off
	s_mov_b32 m0, s48
	s_nop 0
	global_load_lds_dwordx4 v[220:221], off
	s_waitcnt vmcnt(8)
	s_waitcnt lgkmcnt(0)
	s_barrier
; #define PG8_STAGE(bufoff, gbase, voff) do { _Pragma("unroll") for (int _i = 0; _i < 2; ++_i) \
;         __builtin_amdgcn_global_load_lds((const unsigned*)((const char*)(gbase) + (voff)[_i]), (PG8_LAS unsigned*)(lds + (bufoff) + ldsw + _i * 8192), 16, 0, 0); } while (0)
; #define PG8_LDA(dst, b, h) do { _Pragma("unroll") for (int m = 0; m < 4; ++m) _Pragma("unroll") for (int k = 0; k < 2; ++k) dst[m][k] = *(const PG8_LAS bf16x8*)(lds + PG8_SA(b, h) + aoff + m * 2048 + k * 1024); } while (0)
; #define PG8_LDB(dst, b, h) do { _Pragma("unroll") for (int n = 0; n < 2; ++n) _Pragma("unroll") for (int k = 0; k < 2; ++k) dst[n][k] = *(const PG8_LAS bf16x8*)(lds + PG8_SB(b, h) + boff + n * 2048 + k * 1024); } while (0)
; #define PG8_MMA(ai, bj, At, Bt) do { __builtin_amdgcn_s_setprio(1); _Pragma("unroll") for (int m = 0; m < 4; ++m) _Pragma("unroll") for (int n = 0; n < 2; ++n) _Pragma("unroll") for (int k = 0; k < 2; ++k) \
;         acc[ai][bj][m][n] = __builtin_amdgcn_mfma_f32_16x16x32_bf16(Bt[n][k], At[m][k], acc[ai][bj][m][n], 0, 0, 0); __builtin_amdgcn_s_setprio(0); } while (0)
; #define PG8_WAIT_V(n) asm volatile("s_waitcnt vmcnt(" #n ")" ::: "memory")
; #define PG8_WAIT_L(n) asm volatile("s_waitcnt lgkmcnt(" #n ")" ::: "memory")
; #define PG8_BAR __builtin_amdgcn_s_barrier()
; #define PG8_SCHED __builtin_amdgcn_sched_barrier(0)
; template <class Epi, class Sched, bool ALIGN_EPI = false, bool SP2 = false>
; __device__ __forceinline__ void gemm_phase(PG8_LAS unsigned char* lds, const Gemm g, const Sched& S, const Epi& E) {
;     ...
;             PG8_WAIT_V(8); PG8_WAIT_L(0); PG8_BAR; PG8_MMA(1, 0, At, B0); PG8_MMA(1, 1, At, B1); PG8_BAR; PG8_SCHED;
;             PG8_LDB(B0, 1, 0); PG8_LDB(B1, 1, 1); PG8_SCHED; PG8_LDA(At, 1, 0); PG8_STAGE(PG8_SA(0, 1), a2 + hstep, voffA);
;             PG8_WAIT_V(8); PG8_WAIT_L(0); PG8_BAR; PG8_MMA(0, 0, At, B0); PG8_MMA(0, 1, At, B1); PG8_BAR; PG8_SCHED;
	s_setprio 1
	s_waitcnt lgkmcnt(0)
	v_mfma_f32_16x16x32_bf16 v[60:63], v[128:131], v[184:187], v[60:63]
	v_mfma_f32_16x16x32_bf16 v[56:59], v[136:139], v[184:187], v[56:59]
	v_mfma_f32_16x16x32_bf16 v[52:55], v[128:131], v[192:195], v[52:55]
	v_mfma_f32_16x16x32_bf16 v[48:51], v[136:139], v[192:195], v[48:51]
	v_mfma_f32_16x16x32_bf16 v[36:39], v[128:131], v[200:203], v[36:39]
	v_mfma_f32_16x16x32_bf16 v[24:27], v[136:139], v[200:203], v[24:27]
	v_mfma_f32_16x16x32_bf16 v[20:23], v[128:131], v[208:211], v[20:23]
	v_mfma_f32_16x16x32_bf16 v[12:15], v[136:139], v[208:211], v[12:15]
	v_mfma_f32_16x16x32_bf16 v[60:63], v[132:135], v[188:191], v[60:63]
	v_mfma_f32_16x16x32_bf16 v[56:59], v[140:143], v[188:191], v[56:59]
	v_mfma_f32_16x16x32_bf16 v[52:55], v[132:135], v[196:199], v[52:55]
	v_mfma_f32_16x16x32_bf16 v[48:51], v[140:143], v[196:199], v[48:51]
	v_mfma_f32_16x16x32_bf16 v[36:39], v[132:135], v[204:207], v[36:39]
	v_mfma_f32_16x16x32_bf16 v[24:27], v[140:143], v[204:207], v[24:27]
	v_mfma_f32_16x16x32_bf16 v[20:23], v[132:135], v[212:215], v[20:23]
	v_mfma_f32_16x16x32_bf16 v[12:15], v[140:143], v[212:215], v[12:15]
	s_setprio 0
	s_setprio 1
	v_mfma_f32_16x16x32_bf16 v[44:47], v[160:163], v[184:187], v[44:47]
	v_mfma_f32_16x16x32_bf16 v[40:43], v[176:179], v[184:187], v[40:43]
	v_mfma_f32_16x16x32_bf16 v[32:35], v[160:163], v[192:195], v[32:35]
	v_mfma_f32_16x16x32_bf16 v[28:31], v[176:179], v[192:195], v[28:31]
	v_mfma_f32_16x16x32_bf16 v[16:19], v[160:163], v[200:203], v[16:19]
	v_mfma_f32_16x16x32_bf16 v[8:11], v[176:179], v[200:203], v[8:11]
	v_mfma_f32_16x16x32_bf16 v[4:7], v[160:163], v[208:211], v[4:7]
	v_mfma_f32_16x16x32_bf16 v[0:3], v[176:179], v[208:211], v[0:3]
	v_mfma_f32_16x16x32_bf16 v[44:47], v[172:175], v[188:191], v[44:47]
	v_mfma_f32_16x16x32_bf16 v[40:43], v[180:183], v[188:191], v[40:43]
	v_mfma_f32_16x16x32_bf16 v[32:35], v[172:175], v[196:199], v[32:35]
	v_mfma_f32_16x16x32_bf16 v[28:31], v[180:183], v[196:199], v[28:31]
	v_mfma_f32_16x16x32_bf16 v[16:19], v[172:175], v[204:207], v[16:19]
	v_mfma_f32_16x16x32_bf16 v[8:11], v[180:183], v[204:207], v[8:11]
	v_mfma_f32_16x16x32_bf16 v[4:7], v[172:175], v[212:215], v[4:7]
	v_mfma_f32_16x16x32_bf16 v[0:3], v[180:183], v[212:215], v[0:3]
	s_setprio 0
	s_barrier
	s_add_i32 s68, 0, 0x18000
	s_add_i32 s69, 0, 0x1c000
	v_add_u32_e32 v140, s68, v167
	v_add_u32_e32 v180, s69, v167
	ds_read_b128 v[128:131], v140
	ds_read_b128 v[132:135], v140 offset:512
	ds_read_b128 v[136:139], v140 offset:2048
	ds_read_b128 v[140:143], v140 offset:2560
	ds_read_b128 v[160:163], v180
	ds_read_b128 v[172:175], v180 offset:512
	ds_read_b128 v[176:179], v180 offset:2048
	ds_read_b128 v[180:183], v180 offset:2560
	s_add_u32 s40, s40, 0x40000
	s_addc_u32 s41, s41, 0
	s_mov_b32 m0, s49
	v_lshl_add_u64 v[222:223], s[40:41], 0, v[144:145]
	ds_read_b128 v[184:187], v171 offset:32768
	ds_read_b128 v[188:191], v171 offset:33280
	ds_read_b128 v[192:195], v171 offset:34816
	ds_read_b128 v[196:199], v171 offset:35328
	ds_read_b128 v[200:203], v171 offset:36864
	ds_read_b128 v[204:207], v171 offset:37376
	ds_read_b128 v[208:211], v171 offset:38912
	ds_read_b128 v[212:215], v171 offset:39424
	global_load_lds_dwordx4 v[222:223], off
	v_lshl_add_u64 v[222:223], s[40:41], 0, v[148:149]
	s_mov_b32 m0, s50
	s_nop 0
	global_load_lds_dwordx4 v[222:223], off
	s_waitcnt vmcnt(8)
	s_waitcnt lgkmcnt(0)
	s_barrier
	s_setprio 1
	s_waitcnt lgkmcnt(0)
	v_mfma_f32_16x16x32_bf16 v[124:127], v[128:131], v[184:187], v[124:127]
	v_mfma_f32_16x16x32_bf16 v[120:123], v[136:139], v[184:187], v[120:123]
	v_mfma_f32_16x16x32_bf16 v[116:119], v[128:131], v[192:195], v[116:119]
	v_mfma_f32_16x16x32_bf16 v[112:115], v[136:139], v[192:195], v[112:115]
	v_mfma_f32_16x16x32_bf16 v[96:99], v[128:131], v[200:203], v[96:99]
	v_mfma_f32_16x16x32_bf16 v[88:91], v[136:139], v[200:203], v[88:91]
	v_mfma_f32_16x16x32_bf16 v[84:87], v[128:131], v[208:211], v[84:87]
	v_mfma_f32_16x16x32_bf16 v[76:79], v[136:139], v[208:211], v[76:79]
	v_mfma_f32_16x16x32_bf16 v[124:127], v[132:135], v[188:191], v[124:127]
	v_mfma_f32_16x16x32_bf16 v[120:123], v[140:143], v[188:191], v[120:123]
	v_mfma_f32_16x16x32_bf16 v[116:119], v[132:135], v[196:199], v[116:119]
	v_mfma_f32_16x16x32_bf16 v[112:115], v[140:143], v[196:199], v[112:115]
	v_mfma_f32_16x16x32_bf16 v[96:99], v[132:135], v[204:207], v[96:99]
	v_mfma_f32_16x16x32_bf16 v[88:91], v[140:143], v[204:207], v[88:91]
	v_mfma_f32_16x16x32_bf16 v[84:87], v[132:135], v[212:215], v[84:87]
	v_mfma_f32_16x16x32_bf16 v[76:79], v[140:143], v[212:215], v[76:79]
	s_setprio 0
	s_setprio 1
	v_mfma_f32_16x16x32_bf16 v[108:111], v[160:163], v[184:187], v[108:111]
	v_mfma_f32_16x16x32_bf16 v[104:107], v[176:179], v[184:187], v[104:107]
	v_mfma_f32_16x16x32_bf16 v[100:103], v[160:163], v[192:195], v[100:103]
	v_mfma_f32_16x16x32_bf16 v[92:95], v[176:179], v[192:195], v[92:95]
	v_mfma_f32_16x16x32_bf16 v[80:83], v[160:163], v[200:203], v[80:83]
	v_mfma_f32_16x16x32_bf16 v[72:75], v[176:179], v[200:203], v[72:75]
	v_mfma_f32_16x16x32_bf16 v[68:71], v[160:163], v[208:211], v[68:71]
	v_mfma_f32_16x16x32_bf16 v[64:67], v[176:179], v[208:211], v[64:67]
	v_mfma_f32_16x16x32_bf16 v[108:111], v[172:175], v[188:191], v[108:111]
	v_mfma_f32_16x16x32_bf16 v[104:107], v[180:183], v[188:191], v[104:107]
	v_mfma_f32_16x16x32_bf16 v[100:103], v[172:175], v[196:199], v[100:103]
	v_mfma_f32_16x16x32_bf16 v[92:95], v[180:183], v[196:199], v[92:95]
	v_mfma_f32_16x16x32_bf16 v[80:83], v[172:175], v[204:207], v[80:83]
	v_mfma_f32_16x16x32_bf16 v[72:75], v[180:183], v[204:207], v[72:75]
	v_mfma_f32_16x16x32_bf16 v[68:71], v[172:175], v[212:215], v[68:71]
	v_mfma_f32_16x16x32_bf16 v[64:67], v[180:183], v[212:215], v[64:67]
	s_setprio 0
	s_barrier
; #define PG8_STAGE(bufoff, gbase, voff) do { _Pragma("unroll") for (int _i = 0; _i < 2; ++_i) \
;         __builtin_amdgcn_global_load_lds((const unsigned*)((const char*)(gbase) + (voff)[_i]), (PG8_LAS unsigned*)(lds + (bufoff) + ldsw + _i * 8192), 16, 0, 0); } while (0)
; #define PG8_LDA(dst, b, h) do { _Pragma("unroll") for (int m = 0; m < 4; ++m) _Pragma("unroll") for (int k = 0; k < 2; ++k) dst[m][k] = *(const PG8_LAS bf16x8*)(lds + PG8_SA(b, h) + aoff + m * 2048 + k * 1024); } while (0)
; #define PG8_MMA(ai, bj, At, Bt) do { __builtin_amdgcn_s_setprio(1); _Pragma("unroll") for (int m = 0; m < 4; ++m) _Pragma("unroll") for (int n = 0; n < 2; ++n) _Pragma("unroll") for (int k = 0; k < 2; ++k) \
;         acc[ai][bj][m][n] = __builtin_amdgcn_mfma_f32_16x16x32_bf16(Bt[n][k], At[m][k], acc[ai][bj][m][n], 0, 0, 0); __builtin_amdgcn_s_setprio(0); } while (0)
; #define PG8_WAIT_V(n) asm volatile("s_waitcnt vmcnt(" #n ")" ::: "memory")
; #define PG8_WAIT_L(n) asm volatile("s_waitcnt lgkmcnt(" #n ")" ::: "memory")
; #define PG8_BAR __builtin_amdgcn_s_barrier()
; #define PG8_SCHED __builtin_amdgcn_sched_barrier(0)
; template <class Epi, class Sched, bool ALIGN_EPI = false, bool SP2 = false>
; __device__ __forceinline__ void gemm_phase(PG8_LAS unsigned char* lds, const Gemm g, const Sched& S, const Epi& E) {
;     ...
;             PG8_LDA(At, 1, 1); PG8_STAGE(PG8_SB(1, 0), b3, voffB); PG8_STAGE(PG8_SB(1, 1), b3 + hstep, voffB); PG8_STAGE(PG8_SA(1, 0), a3, voffA);
;             PG8_WAIT_V(8); PG8_WAIT_L(0); PG8_BAR; PG8_MMA(1, 0, At, B0); PG8_MMA(1, 1, At, B1); PG8_BAR; PG8_SCHED;
	s_add_i32 s40, s68, s45
	v_lshl_add_u64 v[164:165], v[164:165], 0, s[6:7]
	s_mov_b32 m0, s40
	ds_read_b128 v[184:187], v171 offset:49152
	ds_read_b128 v[188:191], v171 offset:49664
	ds_read_b128 v[192:195], v171 offset:51200
	ds_read_b128 v[196:199], v171 offset:51712
	ds_read_b128 v[200:203], v171 offset:53248
	ds_read_b128 v[204:207], v171 offset:53760
	ds_read_b128 v[208:211], v171 offset:55296
	ds_read_b128 v[212:215], v171 offset:55808
	global_load_lds_dwordx4 v[164:165], off
	s_add_i32 m0, s40, 0x2000
	s_add_u32 s38, s38, 0x40080
	v_lshl_add_u64 v[164:165], v[216:217], 0, s[6:7]
	s_addc_u32 s39, s39, 0
	s_add_i32 s40, s69, s45
	global_load_lds_dwordx4 v[164:165], off
	v_lshl_add_u64 v[164:165], s[38:39], 0, v[146:147]
	s_mov_b32 m0, s40
	s_nop 0
	global_load_lds_dwordx4 v[164:165], off
	v_lshl_add_u64 v[164:165], s[38:39], 0, v[150:151]
	s_add_i32 m0, s40, 0x2000
	s_nop 0
	global_load_lds_dwordx4 v[164:165], off
	v_lshl_add_u64 v[164:165], v[218:219], 0, s[6:7]
	s_mov_b32 m0, s56
	s_nop 0
	global_load_lds_dwordx4 v[164:165], off
	v_lshl_add_u64 v[164:165], v[220:221], 0, s[6:7]
	s_mov_b32 m0, s57
	s_nop 0
	global_load_lds_dwordx4 v[164:165], off
	s_waitcnt vmcnt(8)
	s_waitcnt lgkmcnt(0)
	s_barrier
	s_setprio 1
	s_waitcnt lgkmcnt(0)
	v_mfma_f32_16x16x32_bf16 v[60:63], v[128:131], v[184:187], v[60:63]
	v_mfma_f32_16x16x32_bf16 v[56:59], v[136:139], v[184:187], v[56:59]
	v_mfma_f32_16x16x32_bf16 v[52:55], v[128:131], v[192:195], v[52:55]
	v_mfma_f32_16x16x32_bf16 v[48:51], v[136:139], v[192:195], v[48:51]
	v_mfma_f32_16x16x32_bf16 v[36:39], v[128:131], v[200:203], v[36:39]
	v_mfma_f32_16x16x32_bf16 v[24:27], v[136:139], v[200:203], v[24:27]
	v_mfma_f32_16x16x32_bf16 v[20:23], v[128:131], v[208:211], v[20:23]
	v_mfma_f32_16x16x32_bf16 v[12:15], v[136:139], v[208:211], v[12:15]
	v_mfma_f32_16x16x32_bf16 v[60:63], v[132:135], v[188:191], v[60:63]
	v_mfma_f32_16x16x32_bf16 v[56:59], v[140:143], v[188:191], v[56:59]
	v_mfma_f32_16x16x32_bf16 v[52:55], v[132:135], v[196:199], v[52:55]
	v_mfma_f32_16x16x32_bf16 v[48:51], v[140:143], v[196:199], v[48:51]
	v_mfma_f32_16x16x32_bf16 v[36:39], v[132:135], v[204:207], v[36:39]
	v_mfma_f32_16x16x32_bf16 v[24:27], v[140:143], v[204:207], v[24:27]
	v_mfma_f32_16x16x32_bf16 v[20:23], v[132:135], v[212:215], v[20:23]
	v_mfma_f32_16x16x32_bf16 v[12:15], v[140:143], v[212:215], v[12:15]
	s_setprio 0
	s_setprio 1
	v_mfma_f32_16x16x32_bf16 v[44:47], v[160:163], v[184:187], v[44:47]
	v_mfma_f32_16x16x32_bf16 v[40:43], v[176:179], v[184:187], v[40:43]
	v_mfma_f32_16x16x32_bf16 v[32:35], v[160:163], v[192:195], v[32:35]
	v_mfma_f32_16x16x32_bf16 v[28:31], v[176:179], v[192:195], v[28:31]
	v_mfma_f32_16x16x32_bf16 v[16:19], v[160:163], v[200:203], v[16:19]
	v_mfma_f32_16x16x32_bf16 v[8:11], v[176:179], v[200:203], v[8:11]
	v_mfma_f32_16x16x32_bf16 v[4:7], v[160:163], v[208:211], v[4:7]
	v_mfma_f32_16x16x32_bf16 v[0:3], v[176:179], v[208:211], v[0:3]
	v_mfma_f32_16x16x32_bf16 v[44:47], v[172:175], v[188:191], v[44:47]
	v_mfma_f32_16x16x32_bf16 v[40:43], v[180:183], v[188:191], v[40:43]
	v_mfma_f32_16x16x32_bf16 v[32:35], v[172:175], v[196:199], v[32:35]
	v_mfma_f32_16x16x32_bf16 v[28:31], v[180:183], v[196:199], v[28:31]
	v_mfma_f32_16x16x32_bf16 v[16:19], v[172:175], v[204:207], v[16:19]
	v_mfma_f32_16x16x32_bf16 v[8:11], v[180:183], v[204:207], v[8:11]
	v_mfma_f32_16x16x32_bf16 v[4:7], v[172:175], v[212:215], v[4:7]
	v_mfma_f32_16x16x32_bf16 v[0:3], v[180:183], v[212:215], v[0:3]
	s_setprio 0
	s_add_i32 s65, s65, 2
	s_add_u32 s34, s34, 0x100
	s_addc_u32 s35, s35, 0
	s_add_u32 s63, s63, 0x100
	s_addc_u32 s64, s64, 0
	s_cmp_gt_u32 s65, 13
	s_cbranch_scc1 .Lp4_kexit
	s_barrier
	s_branch .LBB0_457

; #define PG8_STAGE(bufoff, gbase, voff) do { _Pragma("unroll") for (int _i = 0; _i < 2; ++_i) \
;         __builtin_amdgcn_global_load_lds((const unsigned*)((const char*)(gbase) + (voff)[_i]), (PG8_LAS unsigned*)(lds + (bufoff) + ldsw + _i * 8192), 16, 0, 0); } while (0)
; #define PG8_LDA(dst, b, h) do { _Pragma("unroll") for (int m = 0; m < 4; ++m) _Pragma("unroll") for (int k = 0; k < 2; ++k) dst[m][k] = *(const PG8_LAS bf16x8*)(lds + PG8_SA(b, h) + aoff + m * 2048 + k * 1024); } while (0)
; #define PG8_LDB(dst, b, h) do { _Pragma("unroll") for (int n = 0; n < 2; ++n) _Pragma("unroll") for (int k = 0; k < 2; ++k) dst[n][k] = *(const PG8_LAS bf16x8*)(lds + PG8_SB(b, h) + boff + n * 2048 + k * 1024); } while (0)
; #define PG8_MMA(ai, bj, At, Bt) do { __builtin_amdgcn_s_setprio(1); _Pragma("unroll") for (int m = 0; m < 4; ++m) _Pragma("unroll") for (int n = 0; n < 2; ++n) _Pragma("unroll") for (int k = 0; k < 2; ++k) \
;         acc[ai][bj][m][n] = __builtin_amdgcn_mfma_f32_16x16x32_bf16(Bt[n][k], At[m][k], acc[ai][bj][m][n], 0, 0, 0); __builtin_amdgcn_s_setprio(0); } while (0)
; #define PG8_WAIT_V(n) asm volatile("s_waitcnt vmcnt(" #n ")" ::: "memory")
; #define PG8_WAIT_L(n) asm volatile("s_waitcnt lgkmcnt(" #n ")" ::: "memory")
; #define PG8_BAR __builtin_amdgcn_s_barrier()
; #define PG8_SCHED __builtin_amdgcn_sched_barrier(0)
; template <class Epi, class Sched, bool ALIGN_EPI = false, bool SP2 = false>
; __device__ __forceinline__ void gemm_phase(PG8_LAS unsigned char* lds, const Gemm g, const Sched& S, const Epi& E) {
;     ...
;             PG8_LDB(B0, 0, 0); PG8_LDB(B1, 0, 1); PG8_SCHED; PG8_LDA(At, 0, 0); PG8_STAGE(PG8_SA(1, 1), a1 + hstep, voffA);
;             PG8_WAIT_V(8); PG8_WAIT_L(0); PG8_BAR; PG8_MMA(0, 0, At, B0); PG8_MMA(0, 1, At, B1); PG8_BAR; PG8_SCHED;
;             PG8_LDA(At, 0, 1); PG8_STAGE(PG8_SB(0, 0), b2, voffB); PG8_STAGE(PG8_SB(0, 1), b2 + hstep, voffB); PG8_STAGE(PG8_SA(0, 0), a2, voffA);
;             PG8_WAIT_V(8); PG8_WAIT_L(0); PG8_BAR; PG8_MMA(1, 0, At, B0); PG8_MMA(1, 1, At, B1); PG8_BAR; PG8_SCHED;
;     ...
;         for (int a = 0; a < 2; ++a)
; #pragma unroll
;             for (int b = 0; b < 2; ++b)
; #pragma unroll
;                 for (int m = 0; m < 4; ++m)
; #pragma unroll
;                     for (int n = 0; n < 2; ++n) acc[a][b][m][n] = (f32x4){0.f, 0.f, 0.f, 0.f};
.Lp4_peel:
	ds_read_b128 v[128:131], v169
	ds_read_b128 v[132:135], v169 offset:512
	ds_read_b128 v[136:139], v169 offset:2048
	ds_read_b128 v[140:143], v169 offset:2560
	ds_read_b128 v[160:163], v170
	ds_read_b128 v[172:175], v170 offset:512
	ds_read_b128 v[176:179], v170 offset:2048
	ds_read_b128 v[180:183], v170 offset:2560
	s_add_u32 s38, s34, 0xfffc0080
	s_addc_u32 s39, s35, -1
	s_cmp_eq_u32 s65, 12
	s_cselect_b32 s41, s25, s39
	s_cselect_b32 s40, s61, s38
	s_cselect_b32 s39, s21, s64
	s_cselect_b32 s38, s62, s63
	ds_read_b128 v[184:187], v171
	ds_read_b128 v[188:191], v171 offset:512
	ds_read_b128 v[192:195], v171 offset:2048
	ds_read_b128 v[196:199], v171 offset:2560
	ds_read_b128 v[200:203], v171 offset:4096
	ds_read_b128 v[204:207], v171 offset:4608
	ds_read_b128 v[208:211], v171 offset:6144
	ds_read_b128 v[212:215], v171 offset:6656
	s_waitcnt vmcnt(24)
	s_waitcnt lgkmcnt(0)
	s_barrier
	s_setprio 1
	s_waitcnt lgkmcnt(0)
	v_mfma_f32_16x16x32_bf16 v[124:127], v[128:131], v[184:187], 0
	v_mfma_f32_16x16x32_bf16 v[120:123], v[136:139], v[184:187], 0
	v_mfma_f32_16x16x32_bf16 v[116:119], v[128:131], v[192:195], 0
	v_mfma_f32_16x16x32_bf16 v[112:115], v[136:139], v[192:195], 0
	v_mfma_f32_16x16x32_bf16 v[96:99], v[128:131], v[200:203], 0
	v_mfma_f32_16x16x32_bf16 v[88:91], v[136:139], v[200:203], 0
	v_mfma_f32_16x16x32_bf16 v[84:87], v[128:131], v[208:211], 0
	v_mfma_f32_16x16x32_bf16 v[76:79], v[136:139], v[208:211], 0
	v_mfma_f32_16x16x32_bf16 v[124:127], v[132:135], v[188:191], v[124:127]
	v_mfma_f32_16x16x32_bf16 v[120:123], v[140:143], v[188:191], v[120:123]
	v_mfma_f32_16x16x32_bf16 v[116:119], v[132:135], v[196:199], v[116:119]
	v_mfma_f32_16x16x32_bf16 v[112:115], v[140:143], v[196:199], v[112:115]
	v_mfma_f32_16x16x32_bf16 v[96:99], v[132:135], v[204:207], v[96:99]
	v_mfma_f32_16x16x32_bf16 v[88:91], v[140:143], v[204:207], v[88:91]
	v_mfma_f32_16x16x32_bf16 v[84:87], v[132:135], v[212:215], v[84:87]
	v_mfma_f32_16x16x32_bf16 v[76:79], v[140:143], v[212:215], v[76:79]
	s_setprio 0
	s_setprio 1
	v_mfma_f32_16x16x32_bf16 v[108:111], v[160:163], v[184:187], 0
	v_mfma_f32_16x16x32_bf16 v[104:107], v[176:179], v[184:187], 0
	v_mfma_f32_16x16x32_bf16 v[100:103], v[160:163], v[192:195], 0
	v_mfma_f32_16x16x32_bf16 v[92:95], v[176:179], v[192:195], 0
	v_mfma_f32_16x16x32_bf16 v[80:83], v[160:163], v[200:203], 0
	v_mfma_f32_16x16x32_bf16 v[72:75], v[176:179], v[200:203], 0
	v_mfma_f32_16x16x32_bf16 v[68:71], v[160:163], v[208:211], 0
	v_mfma_f32_16x16x32_bf16 v[64:67], v[176:179], v[208:211], 0
	v_mfma_f32_16x16x32_bf16 v[108:111], v[172:175], v[188:191], v[108:111]
	v_mfma_f32_16x16x32_bf16 v[104:107], v[180:183], v[188:191], v[104:107]
	v_mfma_f32_16x16x32_bf16 v[100:103], v[172:175], v[196:199], v[100:103]
	v_mfma_f32_16x16x32_bf16 v[92:95], v[180:183], v[196:199], v[92:95]
	v_mfma_f32_16x16x32_bf16 v[80:83], v[172:175], v[204:207], v[80:83]
	v_mfma_f32_16x16x32_bf16 v[72:75], v[180:183], v[204:207], v[72:75]
	v_mfma_f32_16x16x32_bf16 v[68:71], v[172:175], v[212:215], v[68:71]
	v_mfma_f32_16x16x32_bf16 v[64:67], v[180:183], v[212:215], v[64:67]
	s_setprio 0
	s_barrier
	s_add_i32 s68, s58, s45
	v_lshl_add_u64 v[164:165], s[38:39], 0, v[146:147]
	s_mov_b32 m0, s68
	ds_read_b128 v[184:187], v171 offset:16384
	ds_read_b128 v[188:191], v171 offset:16896
	ds_read_b128 v[192:195], v171 offset:18432
	ds_read_b128 v[196:199], v171 offset:18944
	ds_read_b128 v[200:203], v171 offset:20480
	ds_read_b128 v[204:207], v171 offset:20992
	ds_read_b128 v[208:211], v171 offset:22528
	ds_read_b128 v[212:215], v171 offset:23040
	global_load_lds_dwordx4 v[164:165], off
	s_add_i32 m0, s68, 0x2000
	s_add_u32 s68, s38, 0x40000
	v_lshl_add_u64 v[216:217], s[38:39], 0, v[150:151]
	s_addc_u32 s69, s39, 0
	s_add_i32 s70, s59, s45
	global_load_lds_dwordx4 v[216:217], off
	v_lshl_add_u64 v[218:219], s[68:69], 0, v[146:147]
	s_mov_b32 m0, s70
	v_lshl_add_u64 v[220:221], s[40:41], 0, v[148:149]
	global_load_lds_dwordx4 v[218:219], off
	v_lshl_add_u64 v[218:219], s[68:69], 0, v[150:151]
	s_add_i32 m0, s70, 0x2000
	s_nop 0
	global_load_lds_dwordx4 v[218:219], off
	v_lshl_add_u64 v[218:219], s[40:41], 0, v[144:145]
	s_mov_b32 m0, s31
	s_nop 0
	global_load_lds_dwordx4 v[218:219], off
	s_mov_b32 m0, s48
	s_nop 0
	global_load_lds_dwordx4 v[220:221], off
	s_waitcnt vmcnt(24)
	s_waitcnt lgkmcnt(0)
	s_barrier
	s_setprio 1
	s_waitcnt lgkmcnt(0)
	v_mfma_f32_16x16x32_bf16 v[60:63], v[128:131], v[184:187], 0
	v_mfma_f32_16x16x32_bf16 v[56:59], v[136:139], v[184:187], 0
	v_mfma_f32_16x16x32_bf16 v[52:55], v[128:131], v[192:195], 0
	v_mfma_f32_16x16x32_bf16 v[48:51], v[136:139], v[192:195], 0
	v_mfma_f32_16x16x32_bf16 v[36:39], v[128:131], v[200:203], 0
	v_mfma_f32_16x16x32_bf16 v[24:27], v[136:139], v[200:203], 0
	v_mfma_f32_16x16x32_bf16 v[20:23], v[128:131], v[208:211], 0
	v_mfma_f32_16x16x32_bf16 v[12:15], v[136:139], v[208:211], 0
	v_mfma_f32_16x16x32_bf16 v[60:63], v[132:135], v[188:191], v[60:63]
	v_mfma_f32_16x16x32_bf16 v[56:59], v[140:143], v[188:191], v[56:59]
	v_mfma_f32_16x16x32_bf16 v[52:55], v[132:135], v[196:199], v[52:55]
	v_mfma_f32_16x16x32_bf16 v[48:51], v[140:143], v[196:199], v[48:51]
	v_mfma_f32_16x16x32_bf16 v[36:39], v[132:135], v[204:207], v[36:39]
	v_mfma_f32_16x16x32_bf16 v[24:27], v[140:143], v[204:207], v[24:27]
	v_mfma_f32_16x16x32_bf16 v[20:23], v[132:135], v[212:215], v[20:23]
	v_mfma_f32_16x16x32_bf16 v[12:15], v[140:143], v[212:215], v[12:15]
	s_setprio 0
	s_setprio 1
	v_mfma_f32_16x16x32_bf16 v[44:47], v[160:163], v[184:187], 0
	v_mfma_f32_16x16x32_bf16 v[40:43], v[176:179], v[184:187], 0
	v_mfma_f32_16x16x32_bf16 v[32:35], v[160:163], v[192:195], 0
	v_mfma_f32_16x16x32_bf16 v[28:31], v[176:179], v[192:195], 0
	v_mfma_f32_16x16x32_bf16 v[16:19], v[160:163], v[200:203], 0
	v_mfma_f32_16x16x32_bf16 v[8:11], v[176:179], v[200:203], 0
	v_mfma_f32_16x16x32_bf16 v[4:7], v[160:163], v[208:211], 0
	v_mfma_f32_16x16x32_bf16 v[0:3], v[176:179], v[208:211], 0
	v_mfma_f32_16x16x32_bf16 v[44:47], v[172:175], v[188:191], v[44:47]
	v_mfma_f32_16x16x32_bf16 v[40:43], v[180:183], v[188:191], v[40:43]
	v_mfma_f32_16x16x32_bf16 v[32:35], v[172:175], v[196:199], v[32:35]
	v_mfma_f32_16x16x32_bf16 v[28:31], v[180:183], v[196:199], v[28:31]
	v_mfma_f32_16x16x32_bf16 v[16:19], v[172:175], v[204:207], v[16:19]
	v_mfma_f32_16x16x32_bf16 v[8:11], v[180:183], v[204:207], v[8:11]
	v_mfma_f32_16x16x32_bf16 v[4:7], v[172:175], v[212:215], v[4:7]
	v_mfma_f32_16x16x32_bf16 v[0:3], v[180:183], v[212:215], v[0:3]
	s_setprio 0
	s_barrier
; #define PG8_STAGE(bufoff, gbase, voff) do { _Pragma("unroll") for (int _i = 0; _i < 2; ++_i) \
;         __builtin_amdgcn_global_load_lds((const unsigned*)((const char*)(gbase) + (voff)[_i]), (PG8_LAS unsigned*)(lds + (bufoff) + ldsw + _i * 8192), 16, 0, 0); } while (0)
; #define PG8_LDA(dst, b, h) do { _Pragma("unroll") for (int m = 0; m < 4; ++m) _Pragma("unroll") for (int k = 0; k < 2; ++k) dst[m][k] = *(const PG8_LAS bf16x8*)(lds + PG8_SA(b, h) + aoff + m * 2048 + k * 1024); } while (0)
; #define PG8_LDB(dst, b, h) do { _Pragma("unroll") for (int n = 0; n < 2; ++n) _Pragma("unroll") for (int k = 0; k < 2; ++k) dst[n][k] = *(const PG8_LAS bf16x8*)(lds + PG8_SB(b, h) + boff + n * 2048 + k * 1024); } while (0)
; #define PG8_MMA(ai, bj, At, Bt) do { __builtin_amdgcn_s_setprio(1); _Pragma("unroll") for (int m = 0; m < 4; ++m) _Pragma("unroll") for (int n = 0; n < 2; ++n) _Pragma("unroll") for (int k = 0; k < 2; ++k) \
;         acc[ai][bj][m][n] = __builtin_amdgcn_mfma_f32_16x16x32_bf16(Bt[n][k], At[m][k], acc[ai][bj][m][n], 0, 0, 0); __builtin_amdgcn_s_setprio(0); } while (0)
; #define PG8_WAIT_V(n) asm volatile("s_waitcnt vmcnt(" #n ")" ::: "memory")
; #define PG8_WAIT_L(n) asm volatile("s_waitcnt lgkmcnt(" #n ")" ::: "memory")
; #define PG8_BAR __builtin_amdgcn_s_barrier()
; #define PG8_SCHED __builtin_amdgcn_sched_barrier(0)
; template <class Epi, class Sched, bool ALIGN_EPI = false, bool SP2 = false>
; __device__ __forceinline__ void gemm_phase(PG8_LAS unsigned char* lds, const Gemm g, const Sched& S, const Epi& E) {
;     ...
;             PG8_LDB(B0, 1, 0); PG8_LDB(B1, 1, 1); PG8_SCHED; PG8_LDA(At, 1, 0); PG8_STAGE(PG8_SA(0, 1), a2 + hstep, voffA);
;             PG8_WAIT_V(8); PG8_WAIT_L(0); PG8_BAR; PG8_MMA(0, 0, At, B0); PG8_MMA(0, 1, At, B1); PG8_BAR; PG8_SCHED;
	s_add_i32 s68, 0, 0x18000
	s_add_i32 s69, 0, 0x1c000
	v_add_u32_e32 v140, s68, v167
	v_add_u32_e32 v180, s69, v167
	ds_read_b128 v[128:131], v140
	ds_read_b128 v[132:135], v140 offset:512
	ds_read_b128 v[136:139], v140 offset:2048
	ds_read_b128 v[140:143], v140 offset:2560
	ds_read_b128 v[160:163], v180
	ds_read_b128 v[172:175], v180 offset:512
	ds_read_b128 v[176:179], v180 offset:2048
	ds_read_b128 v[180:183], v180 offset:2560
	s_add_u32 s40, s40, 0x40000
	s_addc_u32 s41, s41, 0
	s_mov_b32 m0, s49
	v_lshl_add_u64 v[222:223], s[40:41], 0, v[144:145]
	ds_read_b128 v[184:187], v171 offset:32768
	ds_read_b128 v[188:191], v171 offset:33280
	ds_read_b128 v[192:195], v171 offset:34816
	ds_read_b128 v[196:199], v171 offset:35328
	ds_read_b128 v[200:203], v171 offset:36864
	ds_read_b128 v[204:207], v171 offset:37376
	ds_read_b128 v[208:211], v171 offset:38912
	ds_read_b128 v[212:215], v171 offset:39424
	global_load_lds_dwordx4 v[222:223], off
	v_lshl_add_u64 v[222:223], s[40:41], 0, v[148:149]
	s_mov_b32 m0, s50
	s_nop 0
	global_load_lds_dwordx4 v[222:223], off
	s_waitcnt vmcnt(24)
	s_waitcnt lgkmcnt(0)
	s_barrier
	s_setprio 1
	s_waitcnt lgkmcnt(0)
	v_mfma_f32_16x16x32_bf16 v[124:127], v[128:131], v[184:187], v[124:127]
	v_mfma_f32_16x16x32_bf16 v[120:123], v[136:139], v[184:187], v[120:123]
	v_mfma_f32_16x16x32_bf16 v[116:119], v[128:131], v[192:195], v[116:119]
	v_mfma_f32_16x16x32_bf16 v[112:115], v[136:139], v[192:195], v[112:115]
	v_mfma_f32_16x16x32_bf16 v[96:99], v[128:131], v[200:203], v[96:99]
	v_mfma_f32_16x16x32_bf16 v[88:91], v[136:139], v[200:203], v[88:91]
	v_mfma_f32_16x16x32_bf16 v[84:87], v[128:131], v[208:211], v[84:87]
	v_mfma_f32_16x16x32_bf16 v[76:79], v[136:139], v[208:211], v[76:79]
	v_mfma_f32_16x16x32_bf16 v[124:127], v[132:135], v[188:191], v[124:127]
	v_mfma_f32_16x16x32_bf16 v[120:123], v[140:143], v[188:191], v[120:123]
	v_mfma_f32_16x16x32_bf16 v[116:119], v[132:135], v[196:199], v[116:119]
	v_mfma_f32_16x16x32_bf16 v[112:115], v[140:143], v[196:199], v[112:115]
	v_mfma_f32_16x16x32_bf16 v[96:99], v[132:135], v[204:207], v[96:99]
	v_mfma_f32_16x16x32_bf16 v[88:91], v[140:143], v[204:207], v[88:91]
	v_mfma_f32_16x16x32_bf16 v[84:87], v[132:135], v[212:215], v[84:87]
	v_mfma_f32_16x16x32_bf16 v[76:79], v[140:143], v[212:215], v[76:79]
	s_setprio 0
	s_setprio 1
	v_mfma_f32_16x16x32_bf16 v[108:111], v[160:163], v[184:187], v[108:111]
	v_mfma_f32_16x16x32_bf16 v[104:107], v[176:179], v[184:187], v[104:107]
	v_mfma_f32_16x16x32_bf16 v[100:103], v[160:163], v[192:195], v[100:103]
	v_mfma_f32_16x16x32_bf16 v[92:95], v[176:179], v[192:195], v[92:95]
	v_mfma_f32_16x16x32_bf16 v[80:83], v[160:163], v[200:203], v[80:83]
	v_mfma_f32_16x16x32_bf16 v[72:75], v[176:179], v[200:203], v[72:75]
	v_mfma_f32_16x16x32_bf16 v[68:71], v[160:163], v[208:211], v[68:71]
	v_mfma_f32_16x16x32_bf16 v[64:67], v[176:179], v[208:211], v[64:67]
	v_mfma_f32_16x16x32_bf16 v[108:111], v[172:175], v[188:191], v[108:111]
	v_mfma_f32_16x16x32_bf16 v[104:107], v[180:183], v[188:191], v[104:107]
	v_mfma_f32_16x16x32_bf16 v[100:103], v[172:175], v[196:199], v[100:103]
	v_mfma_f32_16x16x32_bf16 v[92:95], v[180:183], v[196:199], v[92:95]
	v_mfma_f32_16x16x32_bf16 v[80:83], v[172:175], v[204:207], v[80:83]
	v_mfma_f32_16x16x32_bf16 v[72:75], v[180:183], v[204:207], v[72:75]
	v_mfma_f32_16x16x32_bf16 v[68:71], v[172:175], v[212:215], v[68:71]
	v_mfma_f32_16x16x32_bf16 v[64:67], v[180:183], v[212:215], v[64:67]
	s_setprio 0
	s_barrier
; #define PG8_STAGE(bufoff, gbase, voff) do { _Pragma("unroll") for (int _i = 0; _i < 2; ++_i) \
;         __builtin_amdgcn_global_load_lds((const unsigned*)((const char*)(gbase) + (voff)[_i]), (PG8_LAS unsigned*)(lds + (bufoff) + ldsw + _i * 8192), 16, 0, 0); } while (0)
; #define PG8_LDA(dst, b, h) do { _Pragma("unroll") for (int m = 0; m < 4; ++m) _Pragma("unroll") for (int k = 0; k < 2; ++k) dst[m][k] = *(const PG8_LAS bf16x8*)(lds + PG8_SA(b, h) + aoff + m * 2048 + k * 1024); } while (0)
; #define PG8_MMA(ai, bj, At, Bt) do { __builtin_amdgcn_s_setprio(1); _Pragma("unroll") for (int m = 0; m < 4; ++m) _Pragma("unroll") for (int n = 0; n < 2; ++n) _Pragma("unroll") for (int k = 0; k < 2; ++k) \
;         acc[ai][bj][m][n] = __builtin_amdgcn_mfma_f32_16x16x32_bf16(Bt[n][k], At[m][k], acc[ai][bj][m][n], 0, 0, 0); __builtin_amdgcn_s_setprio(0); } while (0)
; #define PG8_WAIT_V(n) asm volatile("s_waitcnt vmcnt(" #n ")" ::: "memory")
; #define PG8_WAIT_L(n) asm volatile("s_waitcnt lgkmcnt(" #n ")" ::: "memory")
; #define PG8_BAR __builtin_amdgcn_s_barrier()
; #define PG8_SCHED __builtin_amdgcn_sched_barrier(0)
; template <class Epi, class Sched, bool ALIGN_EPI = false, bool SP2 = false>
; __device__ __forceinline__ void gemm_phase(PG8_LAS unsigned char* lds, const Gemm g, const Sched& S, const Epi& E) {
;     ...
;             PG8_LDA(At, 1, 1); PG8_STAGE(PG8_SB(1, 0), b3, voffB); PG8_STAGE(PG8_SB(1, 1), b3 + hstep, voffB); PG8_STAGE(PG8_SA(1, 0), a3, voffA);
;             PG8_WAIT_V(8); PG8_WAIT_L(0); PG8_BAR; PG8_MMA(1, 0, At, B0); PG8_MMA(1, 1, At, B1); PG8_BAR; PG8_SCHED;
	s_add_i32 s40, s68, s45
	v_lshl_add_u64 v[164:165], v[164:165], 0, s[6:7]
	s_mov_b32 m0, s40
	ds_read_b128 v[184:187], v171 offset:49152
	ds_read_b128 v[188:191], v171 offset:49664
	ds_read_b128 v[192:195], v171 offset:51200
	ds_read_b128 v[196:199], v171 offset:51712
	ds_read_b128 v[200:203], v171 offset:53248
	ds_read_b128 v[204:207], v171 offset:53760
	ds_read_b128 v[208:211], v171 offset:55296
	ds_read_b128 v[212:215], v171 offset:55808
	global_load_lds_dwordx4 v[164:165], off
	s_add_i32 m0, s40, 0x2000
	s_add_u32 s38, s38, 0x40080
	v_lshl_add_u64 v[164:165], v[216:217], 0, s[6:7]
	s_addc_u32 s39, s39, 0
	s_add_i32 s40, s69, s45
	global_load_lds_dwordx4 v[164:165], off
	v_lshl_add_u64 v[164:165], s[38:39], 0, v[146:147]
	s_mov_b32 m0, s40
	s_nop 0
	global_load_lds_dwordx4 v[164:165], off
	v_lshl_add_u64 v[164:165], s[38:39], 0, v[150:151]
	s_add_i32 m0, s40, 0x2000
	s_nop 0
	global_load_lds_dwordx4 v[164:165], off
	v_lshl_add_u64 v[164:165], v[218:219], 0, s[6:7]
	s_mov_b32 m0, s56
	s_nop 0
	global_load_lds_dwordx4 v[164:165], off
	v_lshl_add_u64 v[164:165], v[220:221], 0, s[6:7]
	s_mov_b32 m0, s57
	s_nop 0
	global_load_lds_dwordx4 v[164:165], off
	s_waitcnt vmcnt(8)
	s_waitcnt lgkmcnt(0)
	s_barrier
	s_setprio 1
	s_waitcnt lgkmcnt(0)
	v_mfma_f32_16x16x32_bf16 v[60:63], v[128:131], v[184:187], v[60:63]
	v_mfma_f32_16x16x32_bf16 v[56:59], v[136:139], v[184:187], v[56:59]
	v_mfma_f32_16x16x32_bf16 v[52:55], v[128:131], v[192:195], v[52:55]
	v_mfma_f32_16x16x32_bf16 v[48:51], v[136:139], v[192:195], v[48:51]
	v_mfma_f32_16x16x32_bf16 v[36:39], v[128:131], v[200:203], v[36:39]
	v_mfma_f32_16x16x32_bf16 v[24:27], v[136:139], v[200:203], v[24:27]
	v_mfma_f32_16x16x32_bf16 v[20:23], v[128:131], v[208:211], v[20:23]
	v_mfma_f32_16x16x32_bf16 v[12:15], v[136:139], v[208:211], v[12:15]
	v_mfma_f32_16x16x32_bf16 v[60:63], v[132:135], v[188:191], v[60:63]
	v_mfma_f32_16x16x32_bf16 v[56:59], v[140:143], v[188:191], v[56:59]
	v_mfma_f32_16x16x32_bf16 v[52:55], v[132:135], v[196:199], v[52:55]
	v_mfma_f32_16x16x32_bf16 v[48:51], v[140:143], v[196:199], v[48:51]
	v_mfma_f32_16x16x32_bf16 v[36:39], v[132:135], v[204:207], v[36:39]
	v_mfma_f32_16x16x32_bf16 v[24:27], v[140:143], v[204:207], v[24:27]
	v_mfma_f32_16x16x32_bf16 v[20:23], v[132:135], v[212:215], v[20:23]
	v_mfma_f32_16x16x32_bf16 v[12:15], v[140:143], v[212:215], v[12:15]
	s_setprio 0
	s_setprio 1
	v_mfma_f32_16x16x32_bf16 v[44:47], v[160:163], v[184:187], v[44:47]
	v_mfma_f32_16x16x32_bf16 v[40:43], v[176:179], v[184:187], v[40:43]
	v_mfma_f32_16x16x32_bf16 v[32:35], v[160:163], v[192:195], v[32:35]
	v_mfma_f32_16x16x32_bf16 v[28:31], v[176:179], v[192:195], v[28:31]
	v_mfma_f32_16x16x32_bf16 v[16:19], v[160:163], v[200:203], v[16:19]
	v_mfma_f32_16x16x32_bf16 v[8:11], v[176:179], v[200:203], v[8:11]
	v_mfma_f32_16x16x32_bf16 v[4:7], v[160:163], v[208:211], v[4:7]
	v_mfma_f32_16x16x32_bf16 v[0:3], v[176:179], v[208:211], v[0:3]
	v_mfma_f32_16x16x32_bf16 v[44:47], v[172:175], v[188:191], v[44:47]
	v_mfma_f32_16x16x32_bf16 v[40:43], v[180:183], v[188:191], v[40:43]
	v_mfma_f32_16x16x32_bf16 v[32:35], v[172:175], v[196:199], v[32:35]
	v_mfma_f32_16x16x32_bf16 v[28:31], v[180:183], v[196:199], v[28:31]
	v_mfma_f32_16x16x32_bf16 v[16:19], v[172:175], v[204:207], v[16:19]
	v_mfma_f32_16x16x32_bf16 v[8:11], v[180:183], v[204:207], v[8:11]
	v_mfma_f32_16x16x32_bf16 v[4:7], v[172:175], v[212:215], v[4:7]
	v_mfma_f32_16x16x32_bf16 v[0:3], v[180:183], v[212:215], v[0:3]
	s_setprio 0
	s_barrier
	s_add_i32 s65, s65, 2
	s_add_u32 s34, s34, 0x100
	s_addc_u32 s35, s35, 0
	s_add_u32 s63, s63, 0x100
	s_addc_u32 s64, s64, 0
	s_branch .LBB0_457

; __global__ void __launch_bounds__(512, 2) mk_fwd(Params P, int ph_lo, int ph_hi) {
	.amdhsa_kernel _Z6mk_fwd6Paramsii
		.amdhsa_group_segment_fixed_size 0
		.amdhsa_private_segment_fixed_size 0
		.amdhsa_kernarg_size 400
		.amdhsa_user_sgpr_count 2
		.amdhsa_user_sgpr_dispatch_ptr 0
		.amdhsa_user_sgpr_queue_ptr 0
		.amdhsa_user_sgpr_kernarg_segment_ptr 1
		.amdhsa_user_sgpr_dispatch_id 0
		.amdhsa_user_sgpr_kernarg_preload_length 0
		.amdhsa_user_sgpr_kernarg_preload_offset 0
		.amdhsa_user_sgpr_private_segment_size 0
		.amdhsa_uses_dynamic_stack 0
		.amdhsa_enable_private_segment 0
		.amdhsa_system_sgpr_workgroup_id_x 1
		.amdhsa_system_sgpr_workgroup_id_y 0
		.amdhsa_system_sgpr_workgroup_id_z 0
		.amdhsa_system_sgpr_workgroup_info 0
		.amdhsa_system_vgpr_workitem_id 0
		.amdhsa_next_free_vgpr 254
		.amdhsa_next_free_sgpr 100
		.amdhsa_accum_offset 256
		.amdhsa_reserve_vcc 1
		.amdhsa_float_round_mode_32 0
		.amdhsa_float_round_mode_16_64 0
		.amdhsa_float_denorm_mode_32 3
		.amdhsa_float_denorm_mode_16_64 3
		.amdhsa_dx10_clamp 1
		.amdhsa_ieee_mode 1
		.amdhsa_fp16_overflow 0
		.amdhsa_tg_split 0
		.amdhsa_exception_fp_ieee_invalid_op 0
		.amdhsa_exception_fp_denorm_src 0
		.amdhsa_exception_fp_ieee_div_zero 0
		.amdhsa_exception_fp_ieee_overflow 0
		.amdhsa_exception_fp_ieee_underflow 0
		.amdhsa_exception_fp_ieee_inexact 0
		.amdhsa_exception_int_div_zero 0
	.end_amdhsa_kernel

; __global__ void __launch_bounds__(512, 2) mk_fwd(Params P, int ph_lo, int ph_hi) {
amdhsa.kernels:
  - .agpr_count:     0
    .args:
      - .offset:         0
        .size:           136
        .value_kind:     by_value
      - .offset:         136
        .size:           4
        .value_kind:     by_value
      - .offset:         140
        .size:           4
        .value_kind:     by_value
      - .offset:         144
        .size:           4
        .value_kind:     hidden_block_count_x
      - .offset:         148
        .size:           4
        .value_kind:     hidden_block_count_y
      - .offset:         152
        .size:           4
        .value_kind:     hidden_block_count_z
      - .offset:         156
        .size:           2
        .value_kind:     hidden_group_size_x
      - .offset:         158
        .size:           2
        .value_kind:     hidden_group_size_y
      - .offset:         160
        .size:           2
        .value_kind:     hidden_group_size_z
      - .offset:         162
        .size:           2
        .value_kind:     hidden_remainder_x
      - .offset:         164
        .size:           2
        .value_kind:     hidden_remainder_y
      - .offset:         166
        .size:           2
        .value_kind:     hidden_remainder_z
      - .offset:         184
        .size:           8
        .value_kind:     hidden_global_offset_x
      - .offset:         192
        .size:           8
        .value_kind:     hidden_global_offset_y
      - .offset:         200
        .size:           8
        .value_kind:     hidden_global_offset_z
      - .offset:         208
        .size:           2
        .value_kind:     hidden_grid_dims
      - .offset:         264
        .size:           4
        .value_kind:     hidden_dynamic_lds_size
    .group_segment_fixed_size: 0
    .kernarg_segment_align: 8
    .kernarg_segment_size: 400
    .language:       OpenCL C
    .language_version:
      - 2
      - 0
    .max_flat_workgroup_size: 512
    .name:           _Z6mk_fwd6Paramsii
    .private_segment_fixed_size: 0
    .sgpr_count:     106
    .sgpr_spill_count: 4
    .symbol:         _Z6mk_fwd6Paramsii.kd
    .uniform_work_group_size: 1
    .uses_dynamic_stack: false
    .vgpr_count:     254
    .vgpr_spill_count: 0
    .wavefront_size: 64
